# prologue fence v1 plus accumulator zeroing eliminated: first K-loop iteration of every GEMM unit peeled, its first-touch MFMAs take an inline 0 as C operand, 128 v_mov per unit removed (all 4 GEMM loo
# speedup vs baseline: 1.0216x; 1.0216x over previous
; #define PG8_STAGE(bufoff, gbase, voff) do { _Pragma("unroll") for (int _i = 0; _i < 2; ++_i) \
;         __builtin_amdgcn_global_load_lds((const unsigned*)((const char*)(gbase) + (voff)[_i]), (PG8_LAS unsigned*)(lds + (bufoff) + ldsw + _i * 8192), 16, 0, 0); } while (0)
; #define PG8_LDA(dst, b, h) do { _Pragma("unroll") for (int m = 0; m < 4; ++m) _Pragma("unroll") for (int k = 0; k < 2; ++k) dst[m][k] = *(const PG8_LAS bf16x8*)(lds + PG8_SA(b, h) + aoff + m * 2048 + k * 1024); } while (0)
; #define PG8_LDB(dst, b, h) do { _Pragma("unroll") for (int n = 0; n < 2; ++n) _Pragma("unroll") for (int k = 0; k < 2; ++k) dst[n][k] = *(const PG8_LAS bf16x8*)(lds + PG8_SB(b, h) + boff + n * 2048 + k * 1024); } while (0)
; #define PG8_WAIT_V(n) asm volatile("s_waitcnt vmcnt(" #n ")" ::: "memory")
; #define PG8_BAR __builtin_amdgcn_s_barrier()
; template <class Epi, class Sched, bool ALIGN_EPI = false, bool SP2 = false>
; __device__ __forceinline__ void gemm_phase(PG8_LAS unsigned char* lds, const Gemm g, const Sched& S, const Epi& E) {
;     ...
;         const bool has_next = S.next(ui + 1, nxt);
;         const char* nA = has_next ? (const char*)(nxt.sw ? g.A2 : g.A) + (size_t)nxt.pm * tstep : cA; const char* nB = has_next ? (const char*)(nxt.sw ? g.Bt2 : g.Bt) + (size_t)nxt.pn * tstep : cB;
;         for (int t = 0; t < nt; t += 2) {
;             if constexpr (Epi::PF_TRIPS > 0) { if (t == nt - 2 * Epi::PF_TRIPS) E.prefetch(cur, tid, lds + STAGE_BYTES + wid * 512); }
;             const bool last = (t == nt - 2);
;             const char* a1 = cA + (size_t)(t + 1) * kstep;
;             const char* a2 = last ? nA : cA + (size_t)(t + 2) * kstep; const char* b2 = last ? nB : cB + (size_t)(t + 2) * kstep;
;             const char* a3 = a2 + kstep; const char* b3 = b2 + kstep;
;             if (last && has_next) S.a_ready(nxt);
;             if constexpr (SP2) {
;             PG8_LDB(B0, 0, 0); PG8_LDB(B1, 0, 1); PG8_SCHED; PG8_LDA(At, 0, 0); PG8_STAGE(PG8_SA(1, 1), a1 + hstep, voffA);
;             PG8_WAIT_V(8); PG8_WAIT_L(0); PG8_BAR; PG8_MMA(0, 0, At, B0); PG8_MMA(0, 1, At, B1); PG8_BAR; PG8_SCHED;
;             PG8_LDA(At, 0, 1); PG8_STAGE(PG8_SB(0, 0), b2, voffB); PG8_STAGE(PG8_SB(0, 1), b2 + hstep, voffB); PG8_STAGE(PG8_SA(0, 0), a2, voffA);
;             PG8_WAIT_V(8); PG8_WAIT_L(0); PG8_BAR; PG8_MMA(1, 0, At, B0); PG8_MMA(1, 1, At, B1); PG8_BAR; PG8_SCHED;
.LBB0_109:
	s_ashr_i32 s17, s16, 31
	s_lshl_b64 s[18:19], s[16:17], 19
	s_add_u32 s18, s30, s18
	s_addc_u32 s19, s31, s19
	s_and_b64 s[42:43], s[4:5], exec
	s_cselect_b32 s17, s19, s45
	s_cselect_b32 s62, s18, s44
	s_ashr_i32 s15, s14, 31
	s_lshl_b64 s[42:43], s[14:15], 19
	s_add_u32 s42, s20, s42
	s_addc_u32 s43, s38, s43
	s_and_b64 s[48:49], s[4:5], exec
	s_cselect_b32 s15, s43, s47
	s_cselect_b32 s63, s42, s46
	s_add_u32 s44, s44, 0x40080
	s_addc_u32 s45, s45, 0
	s_add_u32 s64, s46, 0x100
	s_addc_u32 s65, s47, 0
	s_mov_b32 s66, -2
	s_add_u32 s46, s44, 0xfffc0080
	s_addc_u32 s47, s45, -1
	s_add_i32 s67, 0, 0x10000
	s_cmp_eq_u32 s66, 12
	s_cselect_b32 s49, s17, s47
	s_cselect_b32 s48, s62, s46
	v_add_u32_e32 v145, s67, v143
	s_cselect_b32 s47, s15, s65
	s_cselect_b32 s46, s63, s64
	s_add_i32 s70, 0, 0x14000
	ds_read_b128 v[146:149], v145
	ds_read_b128 v[150:153], v145 offset:1024
	ds_read_b128 v[154:157], v145 offset:2048
	ds_read_b128 v[158:161], v145 offset:3072
	v_add_u32_e32 v145, s70, v143
	ds_read_b128 v[176:179], v145
	ds_read_b128 v[180:183], v145 offset:1024
	ds_read_b128 v[184:187], v145 offset:2048
	ds_read_b128 v[188:191], v145 offset:3072
	v_lshl_add_u64 v[200:201], s[44:45], 0, v[138:139]
	s_add_i32 m0, s50, 0xc000
	ds_read_b128 v[192:195], v144
	ds_read_b128 v[196:199], v144 offset:1024
	ds_read_b128 v[208:211], v144 offset:2048
	ds_read_b128 v[212:215], v144 offset:3072
	ds_read_b128 v[216:219], v144 offset:4096
	ds_read_b128 v[220:223], v144 offset:5120
	ds_read_b128 v[224:227], v144 offset:6144
	ds_read_b128 v[228:231], v144 offset:7168
	global_load_lds_dwordx4 v[200:201], off
	v_lshl_add_u64 v[200:201], s[44:45], 0, v[140:141]
	s_add_i32 m0, s50, 0xe000
	s_nop 0
	global_load_lds_dwordx4 v[200:201], off
	s_waitcnt vmcnt(8)
	s_waitcnt lgkmcnt(0)
	s_setprio 1
	s_barrier
	v_mfma_f32_16x16x32_bf16 v[126:129], v[146:149], v[192:195], 0
	v_mfma_f32_16x16x32_bf16 v[118:121], v[154:157], v[192:195], 0
	v_mfma_f32_16x16x32_bf16 v[110:113], v[146:149], v[208:211], 0
	v_mfma_f32_16x16x32_bf16 v[102:105], v[154:157], v[208:211], 0
	v_mfma_f32_16x16x32_bf16 v[94:97], v[146:149], v[216:219], 0
	v_mfma_f32_16x16x32_bf16 v[86:89], v[154:157], v[216:219], 0
	v_mfma_f32_16x16x32_bf16 v[76:79], v[146:149], v[224:227], 0
	v_mfma_f32_16x16x32_bf16 v[68:71], v[154:157], v[224:227], 0
	v_mfma_f32_16x16x32_bf16 v[126:129], v[150:153], v[196:199], v[126:129]
	v_mfma_f32_16x16x32_bf16 v[118:121], v[158:161], v[196:199], v[118:121]
	v_mfma_f32_16x16x32_bf16 v[110:113], v[150:153], v[212:215], v[110:113]
	v_mfma_f32_16x16x32_bf16 v[102:105], v[158:161], v[212:215], v[102:105]
	v_mfma_f32_16x16x32_bf16 v[94:97], v[150:153], v[220:223], v[94:97]
	v_mfma_f32_16x16x32_bf16 v[86:89], v[158:161], v[220:223], v[86:89]
	v_mfma_f32_16x16x32_bf16 v[76:79], v[150:153], v[228:231], v[76:79]
	v_mfma_f32_16x16x32_bf16 v[68:71], v[158:161], v[228:231], v[68:71]
	v_mfma_f32_16x16x32_bf16 v[122:125], v[176:179], v[192:195], 0
	v_mfma_f32_16x16x32_bf16 v[114:117], v[184:187], v[192:195], 0
	v_mfma_f32_16x16x32_bf16 v[106:109], v[176:179], v[208:211], 0
	v_mfma_f32_16x16x32_bf16 v[98:101], v[184:187], v[208:211], 0
	v_mfma_f32_16x16x32_bf16 v[90:93], v[176:179], v[216:219], 0
	v_mfma_f32_16x16x32_bf16 v[82:85], v[184:187], v[216:219], 0
	v_mfma_f32_16x16x32_bf16 v[72:75], v[176:179], v[224:227], 0
	v_mfma_f32_16x16x32_bf16 v[64:67], v[184:187], v[224:227], 0
	v_mfma_f32_16x16x32_bf16 v[122:125], v[180:183], v[196:199], v[122:125]
	v_mfma_f32_16x16x32_bf16 v[114:117], v[188:191], v[196:199], v[114:117]
	v_mfma_f32_16x16x32_bf16 v[106:109], v[180:183], v[212:215], v[106:109]
	v_mfma_f32_16x16x32_bf16 v[98:101], v[188:191], v[212:215], v[98:101]
	v_mfma_f32_16x16x32_bf16 v[90:93], v[180:183], v[220:223], v[90:93]
	v_mfma_f32_16x16x32_bf16 v[82:85], v[188:191], v[220:223], v[82:85]
	v_mfma_f32_16x16x32_bf16 v[72:75], v[180:183], v[228:231], v[72:75]
	v_mfma_f32_16x16x32_bf16 v[64:67], v[188:191], v[228:231], v[64:67]
	s_setprio 0
	s_barrier
	s_add_i32 s67, s67, s39
	v_lshl_add_u64 v[200:201], s[46:47], 0, v[134:135]
	s_mov_b32 m0, s67
	ds_read_b128 v[192:195], v144 offset:16384
	ds_read_b128 v[196:199], v144 offset:17408
	ds_read_b128 v[208:211], v144 offset:18432
	ds_read_b128 v[212:215], v144 offset:19456
	ds_read_b128 v[216:219], v144 offset:20480
	ds_read_b128 v[220:223], v144 offset:21504
	ds_read_b128 v[224:227], v144 offset:22528
	ds_read_b128 v[228:231], v144 offset:23552
	global_load_lds_dwordx4 v[200:201], off
	s_add_i32 m0, s67, 0x2000
	s_add_u32 s68, s46, 0x40000
	v_lshl_add_u64 v[232:233], s[46:47], 0, v[130:131]
	s_addc_u32 s69, s47, 0
	s_add_i32 s67, s70, s39
	global_load_lds_dwordx4 v[232:233], off
	v_lshl_add_u64 v[234:235], s[68:69], 0, v[134:135]
	s_mov_b32 m0, s67
	v_lshl_add_u64 v[236:237], s[48:49], 0, v[132:133]
	global_load_lds_dwordx4 v[234:235], off
	v_lshl_add_u64 v[234:235], s[68:69], 0, v[130:131]
	s_add_i32 m0, s67, 0x2000
	s_nop 0
	global_load_lds_dwordx4 v[234:235], off
	v_lshl_add_u64 v[234:235], s[48:49], 0, v[136:137]
	s_mov_b32 m0, s50
	s_nop 0
	global_load_lds_dwordx4 v[234:235], off
	s_mov_b32 m0, s51
	s_nop 0
	global_load_lds_dwordx4 v[236:237], off
	s_waitcnt vmcnt(8)
	s_waitcnt lgkmcnt(0)
	s_setprio 1
	s_barrier
; #define PG8_STAGE(bufoff, gbase, voff) do { _Pragma("unroll") for (int _i = 0; _i < 2; ++_i) \
;         __builtin_amdgcn_global_load_lds((const unsigned*)((const char*)(gbase) + (voff)[_i]), (PG8_LAS unsigned*)(lds + (bufoff) + ldsw + _i * 8192), 16, 0, 0); } while (0)
; #define PG8_LDA(dst, b, h) do { _Pragma("unroll") for (int m = 0; m < 4; ++m) _Pragma("unroll") for (int k = 0; k < 2; ++k) dst[m][k] = *(const PG8_LAS bf16x8*)(lds + PG8_SA(b, h) + aoff + m * 2048 + k * 1024); } while (0)
; #define PG8_LDB(dst, b, h) do { _Pragma("unroll") for (int n = 0; n < 2; ++n) _Pragma("unroll") for (int k = 0; k < 2; ++k) dst[n][k] = *(const PG8_LAS bf16x8*)(lds + PG8_SB(b, h) + boff + n * 2048 + k * 1024); } while (0)
; #define PG8_MMA(ai, bj, At, Bt) do { __builtin_amdgcn_s_setprio(1); _Pragma("unroll") for (int m = 0; m < 4; ++m) _Pragma("unroll") for (int n = 0; n < 2; ++n) _Pragma("unroll") for (int k = 0; k < 2; ++k) \
;         acc[ai][bj][m][n] = __builtin_amdgcn_mfma_f32_16x16x32_bf16(Bt[n][k], At[m][k], acc[ai][bj][m][n], 0, 0, 0); __builtin_amdgcn_s_setprio(0); } while (0)
; #define PG8_WAIT_V(n) asm volatile("s_waitcnt vmcnt(" #n ")" ::: "memory")
; #define PG8_WAIT_L(n) asm volatile("s_waitcnt lgkmcnt(" #n ")" ::: "memory")
; #define PG8_BAR __builtin_amdgcn_s_barrier()
; #define PG8_SCHED __builtin_amdgcn_sched_barrier(0)
; template <class Epi, class Sched, bool ALIGN_EPI = false, bool SP2 = false>
; __device__ __forceinline__ void gemm_phase(PG8_LAS unsigned char* lds, const Gemm g, const Sched& S, const Epi& E) {
;     ...
;             PG8_WAIT_V(8); PG8_WAIT_L(0); PG8_BAR; PG8_MMA(1, 0, At, B0); PG8_MMA(1, 1, At, B1); PG8_BAR; PG8_SCHED;
;             PG8_LDB(B0, 1, 0); PG8_LDB(B1, 1, 1); PG8_SCHED; PG8_LDA(At, 1, 0); PG8_STAGE(PG8_SA(0, 1), a2 + hstep, voffA);
;             PG8_WAIT_V(8); PG8_WAIT_L(0); PG8_BAR; PG8_MMA(0, 0, At, B0); PG8_MMA(0, 1, At, B1); PG8_BAR; PG8_SCHED;
	v_mfma_f32_16x16x32_bf16 v[60:63], v[146:149], v[192:195], 0
	v_mfma_f32_16x16x32_bf16 v[52:55], v[154:157], v[192:195], 0
	v_mfma_f32_16x16x32_bf16 v[44:47], v[146:149], v[208:211], 0
	v_mfma_f32_16x16x32_bf16 v[36:39], v[154:157], v[208:211], 0
	v_mfma_f32_16x16x32_bf16 v[28:31], v[146:149], v[216:219], 0
	v_mfma_f32_16x16x32_bf16 v[20:23], v[154:157], v[216:219], 0
	v_mfma_f32_16x16x32_bf16 v[12:15], v[146:149], v[224:227], 0
	v_mfma_f32_16x16x32_bf16 v[4:7], v[154:157], v[224:227], 0
	v_mfma_f32_16x16x32_bf16 v[60:63], v[150:153], v[196:199], v[60:63]
	v_mfma_f32_16x16x32_bf16 v[52:55], v[158:161], v[196:199], v[52:55]
	v_mfma_f32_16x16x32_bf16 v[44:47], v[150:153], v[212:215], v[44:47]
	v_mfma_f32_16x16x32_bf16 v[36:39], v[158:161], v[212:215], v[36:39]
	v_mfma_f32_16x16x32_bf16 v[28:31], v[150:153], v[220:223], v[28:31]
	v_mfma_f32_16x16x32_bf16 v[20:23], v[158:161], v[220:223], v[20:23]
	v_mfma_f32_16x16x32_bf16 v[12:15], v[150:153], v[228:231], v[12:15]
	v_mfma_f32_16x16x32_bf16 v[4:7], v[158:161], v[228:231], v[4:7]
	v_mfma_f32_16x16x32_bf16 v[56:59], v[176:179], v[192:195], 0
	v_mfma_f32_16x16x32_bf16 v[48:51], v[184:187], v[192:195], 0
	v_mfma_f32_16x16x32_bf16 v[40:43], v[176:179], v[208:211], 0
	v_mfma_f32_16x16x32_bf16 v[32:35], v[184:187], v[208:211], 0
	v_mfma_f32_16x16x32_bf16 v[24:27], v[176:179], v[216:219], 0
	v_mfma_f32_16x16x32_bf16 v[16:19], v[184:187], v[216:219], 0
	v_mfma_f32_16x16x32_bf16 v[8:11], v[176:179], v[224:227], 0
	v_mfma_f32_16x16x32_bf16 v[0:3], v[184:187], v[224:227], 0
	v_mfma_f32_16x16x32_bf16 v[56:59], v[180:183], v[196:199], v[56:59]
	v_mfma_f32_16x16x32_bf16 v[48:51], v[188:191], v[196:199], v[48:51]
	v_mfma_f32_16x16x32_bf16 v[40:43], v[180:183], v[212:215], v[40:43]
	v_mfma_f32_16x16x32_bf16 v[32:35], v[188:191], v[212:215], v[32:35]
	v_mfma_f32_16x16x32_bf16 v[24:27], v[180:183], v[220:223], v[24:27]
	v_mfma_f32_16x16x32_bf16 v[16:19], v[188:191], v[220:223], v[16:19]
	v_mfma_f32_16x16x32_bf16 v[8:11], v[180:183], v[228:231], v[8:11]
	v_mfma_f32_16x16x32_bf16 v[0:3], v[188:191], v[228:231], v[0:3]
	s_setprio 0
	s_barrier
	s_add_i32 s67, 0, 0x18000
	v_add_u32_e32 v145, s67, v143
	s_add_i32 s68, 0, 0x1c000
	ds_read_b128 v[146:149], v145
	ds_read_b128 v[150:153], v145 offset:1024
	ds_read_b128 v[154:157], v145 offset:2048
	ds_read_b128 v[158:161], v145 offset:3072
	v_add_u32_e32 v145, s68, v143
	ds_read_b128 v[176:179], v145
	ds_read_b128 v[180:183], v145 offset:1024
	ds_read_b128 v[184:187], v145 offset:2048
	ds_read_b128 v[188:191], v145 offset:3072
	s_add_u32 s48, s48, 0x40000
	s_addc_u32 s49, s49, 0
	s_mov_b32 m0, s52
	v_lshl_add_u64 v[238:239], s[48:49], 0, v[136:137]
	ds_read_b128 v[192:195], v144 offset:32768
	ds_read_b128 v[196:199], v144 offset:33792
	ds_read_b128 v[208:211], v144 offset:34816
	ds_read_b128 v[212:215], v144 offset:35840
	ds_read_b128 v[216:219], v144 offset:36864
	ds_read_b128 v[220:223], v144 offset:37888
	ds_read_b128 v[224:227], v144 offset:38912
	ds_read_b128 v[228:231], v144 offset:39936
	global_load_lds_dwordx4 v[238:239], off
	v_lshl_add_u64 v[238:239], s[48:49], 0, v[132:133]
	s_mov_b32 m0, s53
	s_nop 0
	global_load_lds_dwordx4 v[238:239], off
	s_waitcnt vmcnt(8)
	s_waitcnt lgkmcnt(0)
	s_setprio 1
	s_barrier
	v_mfma_f32_16x16x32_bf16 v[126:129], v[146:149], v[192:195], v[126:129]
	v_mfma_f32_16x16x32_bf16 v[118:121], v[154:157], v[192:195], v[118:121]
	v_mfma_f32_16x16x32_bf16 v[110:113], v[146:149], v[208:211], v[110:113]
	v_mfma_f32_16x16x32_bf16 v[102:105], v[154:157], v[208:211], v[102:105]
	v_mfma_f32_16x16x32_bf16 v[94:97], v[146:149], v[216:219], v[94:97]
	v_mfma_f32_16x16x32_bf16 v[86:89], v[154:157], v[216:219], v[86:89]
	v_mfma_f32_16x16x32_bf16 v[76:79], v[146:149], v[224:227], v[76:79]
	v_mfma_f32_16x16x32_bf16 v[68:71], v[154:157], v[224:227], v[68:71]
	v_mfma_f32_16x16x32_bf16 v[126:129], v[150:153], v[196:199], v[126:129]
	v_mfma_f32_16x16x32_bf16 v[118:121], v[158:161], v[196:199], v[118:121]
	v_mfma_f32_16x16x32_bf16 v[110:113], v[150:153], v[212:215], v[110:113]
	v_mfma_f32_16x16x32_bf16 v[102:105], v[158:161], v[212:215], v[102:105]
	v_mfma_f32_16x16x32_bf16 v[94:97], v[150:153], v[220:223], v[94:97]
	v_mfma_f32_16x16x32_bf16 v[86:89], v[158:161], v[220:223], v[86:89]
	v_mfma_f32_16x16x32_bf16 v[76:79], v[150:153], v[228:231], v[76:79]
	v_mfma_f32_16x16x32_bf16 v[68:71], v[158:161], v[228:231], v[68:71]
	v_mfma_f32_16x16x32_bf16 v[122:125], v[176:179], v[192:195], v[122:125]
	v_mfma_f32_16x16x32_bf16 v[114:117], v[184:187], v[192:195], v[114:117]
	v_mfma_f32_16x16x32_bf16 v[106:109], v[176:179], v[208:211], v[106:109]
	v_mfma_f32_16x16x32_bf16 v[98:101], v[184:187], v[208:211], v[98:101]
	v_mfma_f32_16x16x32_bf16 v[90:93], v[176:179], v[216:219], v[90:93]
	v_mfma_f32_16x16x32_bf16 v[82:85], v[184:187], v[216:219], v[82:85]
	v_mfma_f32_16x16x32_bf16 v[72:75], v[176:179], v[224:227], v[72:75]
	v_mfma_f32_16x16x32_bf16 v[64:67], v[184:187], v[224:227], v[64:67]
	v_mfma_f32_16x16x32_bf16 v[122:125], v[180:183], v[196:199], v[122:125]
	v_mfma_f32_16x16x32_bf16 v[114:117], v[188:191], v[196:199], v[114:117]
	v_mfma_f32_16x16x32_bf16 v[106:109], v[180:183], v[212:215], v[106:109]
	v_mfma_f32_16x16x32_bf16 v[98:101], v[188:191], v[212:215], v[98:101]
	v_mfma_f32_16x16x32_bf16 v[90:93], v[180:183], v[220:223], v[90:93]
	v_mfma_f32_16x16x32_bf16 v[82:85], v[188:191], v[220:223], v[82:85]
	v_mfma_f32_16x16x32_bf16 v[72:75], v[180:183], v[228:231], v[72:75]
	v_mfma_f32_16x16x32_bf16 v[64:67], v[188:191], v[228:231], v[64:67]
	s_setprio 0
	s_barrier
; #define PG8_STAGE(bufoff, gbase, voff) do { _Pragma("unroll") for (int _i = 0; _i < 2; ++_i) \
;         __builtin_amdgcn_global_load_lds((const unsigned*)((const char*)(gbase) + (voff)[_i]), (PG8_LAS unsigned*)(lds + (bufoff) + ldsw + _i * 8192), 16, 0, 0); } while (0)
; #define PG8_LDA(dst, b, h) do { _Pragma("unroll") for (int m = 0; m < 4; ++m) _Pragma("unroll") for (int k = 0; k < 2; ++k) dst[m][k] = *(const PG8_LAS bf16x8*)(lds + PG8_SA(b, h) + aoff + m * 2048 + k * 1024); } while (0)
; #define PG8_MMA(ai, bj, At, Bt) do { __builtin_amdgcn_s_setprio(1); _Pragma("unroll") for (int m = 0; m < 4; ++m) _Pragma("unroll") for (int n = 0; n < 2; ++n) _Pragma("unroll") for (int k = 0; k < 2; ++k) \
;         acc[ai][bj][m][n] = __builtin_amdgcn_mfma_f32_16x16x32_bf16(Bt[n][k], At[m][k], acc[ai][bj][m][n], 0, 0, 0); __builtin_amdgcn_s_setprio(0); } while (0)
; #define PG8_WAIT_V(n) asm volatile("s_waitcnt vmcnt(" #n ")" ::: "memory")
; #define PG8_WAIT_L(n) asm volatile("s_waitcnt lgkmcnt(" #n ")" ::: "memory")
; #define PG8_BAR __builtin_amdgcn_s_barrier()
; #define PG8_SCHED __builtin_amdgcn_sched_barrier(0)
; template <class Epi, class Sched, bool ALIGN_EPI = false, bool SP2 = false>
; __device__ __forceinline__ void gemm_phase(PG8_LAS unsigned char* lds, const Gemm g, const Sched& S, const Epi& E) {
;     ...
;             PG8_LDA(At, 1, 1); PG8_STAGE(PG8_SB(1, 0), b3, voffB); PG8_STAGE(PG8_SB(1, 1), b3 + hstep, voffB); PG8_STAGE(PG8_SA(1, 0), a3, voffA);
;             PG8_WAIT_V(8); PG8_WAIT_L(0); PG8_BAR; PG8_MMA(1, 0, At, B0); PG8_MMA(1, 1, At, B1); PG8_BAR; PG8_SCHED;
	s_add_i32 s48, s67, s39
	v_lshl_add_u64 v[200:201], v[200:201], 0, s[40:41]
	s_mov_b32 m0, s48
	ds_read_b128 v[192:195], v144 offset:49152
	ds_read_b128 v[196:199], v144 offset:50176
	ds_read_b128 v[208:211], v144 offset:51200
	ds_read_b128 v[212:215], v144 offset:52224
	ds_read_b128 v[216:219], v144 offset:53248
	ds_read_b128 v[220:223], v144 offset:54272
	ds_read_b128 v[224:227], v144 offset:55296
	ds_read_b128 v[228:231], v144 offset:56320
	global_load_lds_dwordx4 v[200:201], off
	s_add_i32 m0, s48, 0x2000
	s_add_u32 s46, s46, 0x40080
	v_lshl_add_u64 v[200:201], v[232:233], 0, s[40:41]
	s_addc_u32 s47, s47, 0
	s_add_i32 s48, s68, s39
	global_load_lds_dwordx4 v[200:201], off
	v_lshl_add_u64 v[200:201], s[46:47], 0, v[134:135]
	s_mov_b32 m0, s48
	s_nop 0
	global_load_lds_dwordx4 v[200:201], off
	v_lshl_add_u64 v[200:201], s[46:47], 0, v[130:131]
	s_add_i32 m0, s48, 0x2000
	s_nop 0
	global_load_lds_dwordx4 v[200:201], off
	v_lshl_add_u64 v[200:201], v[234:235], 0, s[40:41]
	s_mov_b32 m0, s56
	s_nop 0
	global_load_lds_dwordx4 v[200:201], off
	v_lshl_add_u64 v[200:201], v[236:237], 0, s[40:41]
	s_mov_b32 m0, s57
	s_nop 0
	global_load_lds_dwordx4 v[200:201], off
	s_waitcnt vmcnt(8)
	s_waitcnt lgkmcnt(0)
	s_setprio 1
	s_barrier
	v_mfma_f32_16x16x32_bf16 v[60:63], v[146:149], v[192:195], v[60:63]
	v_mfma_f32_16x16x32_bf16 v[52:55], v[154:157], v[192:195], v[52:55]
	v_mfma_f32_16x16x32_bf16 v[44:47], v[146:149], v[208:211], v[44:47]
	v_mfma_f32_16x16x32_bf16 v[36:39], v[154:157], v[208:211], v[36:39]
	v_mfma_f32_16x16x32_bf16 v[28:31], v[146:149], v[216:219], v[28:31]
	v_mfma_f32_16x16x32_bf16 v[20:23], v[154:157], v[216:219], v[20:23]
	v_mfma_f32_16x16x32_bf16 v[12:15], v[146:149], v[224:227], v[12:15]
	v_mfma_f32_16x16x32_bf16 v[4:7], v[154:157], v[224:227], v[4:7]
	v_mfma_f32_16x16x32_bf16 v[60:63], v[150:153], v[196:199], v[60:63]
	v_mfma_f32_16x16x32_bf16 v[52:55], v[158:161], v[196:199], v[52:55]
	v_mfma_f32_16x16x32_bf16 v[44:47], v[150:153], v[212:215], v[44:47]
	v_mfma_f32_16x16x32_bf16 v[36:39], v[158:161], v[212:215], v[36:39]
	v_mfma_f32_16x16x32_bf16 v[28:31], v[150:153], v[220:223], v[28:31]
	v_mfma_f32_16x16x32_bf16 v[20:23], v[158:161], v[220:223], v[20:23]
	v_mfma_f32_16x16x32_bf16 v[12:15], v[150:153], v[228:231], v[12:15]
	v_mfma_f32_16x16x32_bf16 v[4:7], v[158:161], v[228:231], v[4:7]
	v_mfma_f32_16x16x32_bf16 v[56:59], v[176:179], v[192:195], v[56:59]
	v_mfma_f32_16x16x32_bf16 v[48:51], v[184:187], v[192:195], v[48:51]
	v_mfma_f32_16x16x32_bf16 v[40:43], v[176:179], v[208:211], v[40:43]
	v_mfma_f32_16x16x32_bf16 v[32:35], v[184:187], v[208:211], v[32:35]
	v_mfma_f32_16x16x32_bf16 v[24:27], v[176:179], v[216:219], v[24:27]
	v_mfma_f32_16x16x32_bf16 v[16:19], v[184:187], v[216:219], v[16:19]
	v_mfma_f32_16x16x32_bf16 v[8:11], v[176:179], v[224:227], v[8:11]
	v_mfma_f32_16x16x32_bf16 v[0:3], v[184:187], v[224:227], v[0:3]
	v_mfma_f32_16x16x32_bf16 v[56:59], v[180:183], v[196:199], v[56:59]
	v_mfma_f32_16x16x32_bf16 v[48:51], v[188:191], v[196:199], v[48:51]
	v_mfma_f32_16x16x32_bf16 v[40:43], v[180:183], v[212:215], v[40:43]
	v_mfma_f32_16x16x32_bf16 v[32:35], v[188:191], v[212:215], v[32:35]
	v_mfma_f32_16x16x32_bf16 v[24:27], v[180:183], v[220:223], v[24:27]
	v_mfma_f32_16x16x32_bf16 v[16:19], v[188:191], v[220:223], v[16:19]
	v_mfma_f32_16x16x32_bf16 v[8:11], v[180:183], v[228:231], v[8:11]
	v_mfma_f32_16x16x32_bf16 v[0:3], v[188:191], v[228:231], v[0:3]
	s_setprio 0
	s_barrier
	s_add_i32 s66, s66, 2
	s_add_u32 s44, s44, 0x100
	s_addc_u32 s45, s45, 0
	s_add_u32 s64, s64, 0x100
	s_addc_u32 s65, s65, 0
	s_cmp_gt_u32 s66, 13
	s_cbranch_scc1 .Lpeel_exit_0

; #define PG8_STAGE(bufoff, gbase, voff) do { _Pragma("unroll") for (int _i = 0; _i < 2; ++_i) \
;         __builtin_amdgcn_global_load_lds((const unsigned*)((const char*)(gbase) + (voff)[_i]), (PG8_LAS unsigned*)(lds + (bufoff) + ldsw + _i * 8192), 16, 0, 0); } while (0)
; #define PG8_LDA(dst, b, h) do { _Pragma("unroll") for (int m = 0; m < 4; ++m) _Pragma("unroll") for (int k = 0; k < 2; ++k) dst[m][k] = *(const PG8_LAS bf16x8*)(lds + PG8_SA(b, h) + aoff + m * 2048 + k * 1024); } while (0)
; #define PG8_LDB(dst, b, h) do { _Pragma("unroll") for (int n = 0; n < 2; ++n) _Pragma("unroll") for (int k = 0; k < 2; ++k) dst[n][k] = *(const PG8_LAS bf16x8*)(lds + PG8_SB(b, h) + boff + n * 2048 + k * 1024); } while (0)
; #define PG8_WAIT_V(n) asm volatile("s_waitcnt vmcnt(" #n ")" ::: "memory")
; #define PG8_BAR __builtin_amdgcn_s_barrier()
; template <class Epi, class Sched, bool ALIGN_EPI = false, bool SP2 = false>
; __device__ __forceinline__ void gemm_phase(PG8_LAS unsigned char* lds, const Gemm g, const Sched& S, const Epi& E) {
;     ...
;         const bool has_next = S.next(ui + 1, nxt);
;         const char* nA = has_next ? (const char*)(nxt.sw ? g.A2 : g.A) + (size_t)nxt.pm * tstep : cA; const char* nB = has_next ? (const char*)(nxt.sw ? g.Bt2 : g.Bt) + (size_t)nxt.pn * tstep : cB;
;         for (int t = 0; t < nt; t += 2) {
;             if constexpr (Epi::PF_TRIPS > 0) { if (t == nt - 2 * Epi::PF_TRIPS) E.prefetch(cur, tid, lds + STAGE_BYTES + wid * 512); }
;             const bool last = (t == nt - 2);
;             const char* a1 = cA + (size_t)(t + 1) * kstep;
;             const char* a2 = last ? nA : cA + (size_t)(t + 2) * kstep; const char* b2 = last ? nB : cB + (size_t)(t + 2) * kstep;
;             const char* a3 = a2 + kstep; const char* b3 = b2 + kstep;
;             if (last && has_next) S.a_ready(nxt);
;             if constexpr (SP2) {
;             PG8_LDB(B0, 0, 0); PG8_LDB(B1, 0, 1); PG8_SCHED; PG8_LDA(At, 0, 0); PG8_STAGE(PG8_SA(1, 1), a1 + hstep, voffA);
;             PG8_WAIT_V(8); PG8_WAIT_L(0); PG8_BAR; PG8_MMA(0, 0, At, B0); PG8_MMA(0, 1, At, B1); PG8_BAR; PG8_SCHED;
;             PG8_LDA(At, 0, 1); PG8_STAGE(PG8_SB(0, 0), b2, voffB); PG8_STAGE(PG8_SB(0, 1), b2 + hstep, voffB); PG8_STAGE(PG8_SA(0, 0), a2, voffA);
;             PG8_WAIT_V(8); PG8_WAIT_L(0); PG8_BAR; PG8_MMA(1, 0, At, B0); PG8_MMA(1, 1, At, B1); PG8_BAR; PG8_SCHED;
.LBB0_128:
	s_ashr_i32 s19, s18, 31
	s_lshl_b64 s[42:43], s[18:19], 19
	s_add_u32 s42, s30, s42
	s_addc_u32 s43, s31, s43
	s_and_b64 s[44:45], s[4:5], exec
	s_cselect_b32 s19, s43, s47
	s_cselect_b32 s64, s42, s46
	s_ashr_i32 s17, s16, 31
	s_lshl_b64 s[44:45], s[16:17], 19
	s_add_u32 s44, s38, s44
	s_addc_u32 s45, s39, s45
	s_and_b64 s[50:51], s[4:5], exec
	s_cselect_b32 s17, s45, s49
	s_cselect_b32 s65, s44, s48
	s_add_u32 s46, s46, 0x40080
	s_addc_u32 s47, s47, 0
	s_add_u32 s66, s48, 0x100
	s_addc_u32 s67, s49, 0
	s_mov_b32 s68, -2
	s_add_u32 s48, s46, 0xfffc0080
	s_addc_u32 s49, s47, -1
	s_add_i32 s69, 0, 0x10000
	s_cmp_eq_u32 s68, 12
	s_cselect_b32 s51, s19, s49
	s_cselect_b32 s50, s64, s48
	v_add_u32_e32 v142, s69, v148
	s_cselect_b32 s49, s17, s67
	s_cselect_b32 s48, s65, s66
	s_add_i32 s72, 0, 0x14000
	ds_read_b128 v[150:153], v142
	ds_read_b128 v[154:157], v142 offset:1024
	ds_read_b128 v[158:161], v142 offset:2048
	ds_read_b128 v[176:179], v142 offset:3072
	v_add_u32_e32 v142, s72, v148
	ds_read_b128 v[180:183], v142
	ds_read_b128 v[184:187], v142 offset:1024
	ds_read_b128 v[188:191], v142 offset:2048
	ds_read_b128 v[192:195], v142 offset:3072
	v_lshl_add_u64 v[142:143], s[46:47], 0, v[138:139]
	s_add_i32 m0, s53, 0xc000
	ds_read_b128 v[196:199], v149
	ds_read_b128 v[208:211], v149 offset:1024
	ds_read_b128 v[212:215], v149 offset:2048
	ds_read_b128 v[216:219], v149 offset:3072
	ds_read_b128 v[220:223], v149 offset:4096
	ds_read_b128 v[224:227], v149 offset:5120
	ds_read_b128 v[228:231], v149 offset:6144
	ds_read_b128 v[232:235], v149 offset:7168
	global_load_lds_dwordx4 v[142:143], off
	v_lshl_add_u64 v[142:143], s[46:47], 0, v[140:141]
	s_add_i32 m0, s53, 0xe000
	s_nop 0
	global_load_lds_dwordx4 v[142:143], off
	s_waitcnt vmcnt(8)
	s_waitcnt lgkmcnt(0)
	s_setprio 1
	s_barrier
	v_mfma_f32_16x16x32_bf16 v[126:129], v[150:153], v[196:199], 0
	v_mfma_f32_16x16x32_bf16 v[122:125], v[158:161], v[196:199], 0
	v_mfma_f32_16x16x32_bf16 v[114:117], v[150:153], v[212:215], 0
	v_mfma_f32_16x16x32_bf16 v[106:109], v[158:161], v[212:215], 0
	v_mfma_f32_16x16x32_bf16 v[98:101], v[150:153], v[220:223], 0
	v_mfma_f32_16x16x32_bf16 v[90:93], v[158:161], v[220:223], 0
	v_mfma_f32_16x16x32_bf16 v[82:85], v[150:153], v[228:231], 0
	v_mfma_f32_16x16x32_bf16 v[72:75], v[158:161], v[228:231], 0
	v_mfma_f32_16x16x32_bf16 v[126:129], v[154:157], v[208:211], v[126:129]
	v_mfma_f32_16x16x32_bf16 v[122:125], v[176:179], v[208:211], v[122:125]
	v_mfma_f32_16x16x32_bf16 v[114:117], v[154:157], v[216:219], v[114:117]
	v_mfma_f32_16x16x32_bf16 v[106:109], v[176:179], v[216:219], v[106:109]
	v_mfma_f32_16x16x32_bf16 v[98:101], v[154:157], v[224:227], v[98:101]
	v_mfma_f32_16x16x32_bf16 v[90:93], v[176:179], v[224:227], v[90:93]
	v_mfma_f32_16x16x32_bf16 v[82:85], v[154:157], v[232:235], v[82:85]
	v_mfma_f32_16x16x32_bf16 v[72:75], v[176:179], v[232:235], v[72:75]
	v_mfma_f32_16x16x32_bf16 v[118:121], v[180:183], v[196:199], 0
	v_mfma_f32_16x16x32_bf16 v[110:113], v[188:191], v[196:199], 0
	v_mfma_f32_16x16x32_bf16 v[102:105], v[180:183], v[212:215], 0
	v_mfma_f32_16x16x32_bf16 v[94:97], v[188:191], v[212:215], 0
	v_mfma_f32_16x16x32_bf16 v[86:89], v[180:183], v[220:223], 0
	v_mfma_f32_16x16x32_bf16 v[76:79], v[188:191], v[220:223], 0
	v_mfma_f32_16x16x32_bf16 v[68:71], v[180:183], v[228:231], 0
	v_mfma_f32_16x16x32_bf16 v[64:67], v[188:191], v[228:231], 0
	v_mfma_f32_16x16x32_bf16 v[118:121], v[184:187], v[208:211], v[118:121]
	v_mfma_f32_16x16x32_bf16 v[110:113], v[192:195], v[208:211], v[110:113]
	v_mfma_f32_16x16x32_bf16 v[102:105], v[184:187], v[216:219], v[102:105]
	v_mfma_f32_16x16x32_bf16 v[94:97], v[192:195], v[216:219], v[94:97]
	v_mfma_f32_16x16x32_bf16 v[86:89], v[184:187], v[224:227], v[86:89]
	v_mfma_f32_16x16x32_bf16 v[76:79], v[192:195], v[224:227], v[76:79]
	v_mfma_f32_16x16x32_bf16 v[68:71], v[184:187], v[232:235], v[68:71]
	v_mfma_f32_16x16x32_bf16 v[64:67], v[192:195], v[232:235], v[64:67]
	s_setprio 0
	s_barrier
	s_add_i32 s69, s69, s52
	v_lshl_add_u64 v[142:143], s[48:49], 0, v[134:135]
	s_mov_b32 m0, s69
	ds_read_b128 v[196:199], v149 offset:16384
	ds_read_b128 v[208:211], v149 offset:17408
	ds_read_b128 v[212:215], v149 offset:18432
	ds_read_b128 v[216:219], v149 offset:19456
	ds_read_b128 v[220:223], v149 offset:20480
	ds_read_b128 v[224:227], v149 offset:21504
	ds_read_b128 v[228:231], v149 offset:22528
	ds_read_b128 v[232:235], v149 offset:23552
	global_load_lds_dwordx4 v[142:143], off
	s_add_i32 m0, s69, 0x2000
	s_add_u32 s70, s48, 0x40000
	v_lshl_add_u64 v[146:147], s[48:49], 0, v[130:131]
	s_addc_u32 s71, s49, 0
	s_add_i32 s69, s72, s52
	global_load_lds_dwordx4 v[146:147], off
	v_lshl_add_u64 v[200:201], s[70:71], 0, v[134:135]
	s_mov_b32 m0, s69
	v_lshl_add_u64 v[236:237], s[50:51], 0, v[132:133]
	global_load_lds_dwordx4 v[200:201], off
	v_lshl_add_u64 v[200:201], s[70:71], 0, v[130:131]
	s_add_i32 m0, s69, 0x2000
	s_nop 0
	global_load_lds_dwordx4 v[200:201], off
	v_lshl_add_u64 v[200:201], s[50:51], 0, v[136:137]
	s_mov_b32 m0, s53
	s_nop 0
	global_load_lds_dwordx4 v[200:201], off
	s_mov_b32 m0, s54
	s_nop 0
	global_load_lds_dwordx4 v[236:237], off
	s_waitcnt vmcnt(8)
	s_waitcnt lgkmcnt(0)
	s_setprio 1
	s_barrier
; #define PG8_STAGE(bufoff, gbase, voff) do { _Pragma("unroll") for (int _i = 0; _i < 2; ++_i) \
;         __builtin_amdgcn_global_load_lds((const unsigned*)((const char*)(gbase) + (voff)[_i]), (PG8_LAS unsigned*)(lds + (bufoff) + ldsw + _i * 8192), 16, 0, 0); } while (0)
; #define PG8_LDA(dst, b, h) do { _Pragma("unroll") for (int m = 0; m < 4; ++m) _Pragma("unroll") for (int k = 0; k < 2; ++k) dst[m][k] = *(const PG8_LAS bf16x8*)(lds + PG8_SA(b, h) + aoff + m * 2048 + k * 1024); } while (0)
; #define PG8_LDB(dst, b, h) do { _Pragma("unroll") for (int n = 0; n < 2; ++n) _Pragma("unroll") for (int k = 0; k < 2; ++k) dst[n][k] = *(const PG8_LAS bf16x8*)(lds + PG8_SB(b, h) + boff + n * 2048 + k * 1024); } while (0)
; #define PG8_MMA(ai, bj, At, Bt) do { __builtin_amdgcn_s_setprio(1); _Pragma("unroll") for (int m = 0; m < 4; ++m) _Pragma("unroll") for (int n = 0; n < 2; ++n) _Pragma("unroll") for (int k = 0; k < 2; ++k) \
;         acc[ai][bj][m][n] = __builtin_amdgcn_mfma_f32_16x16x32_bf16(Bt[n][k], At[m][k], acc[ai][bj][m][n], 0, 0, 0); __builtin_amdgcn_s_setprio(0); } while (0)
; #define PG8_WAIT_V(n) asm volatile("s_waitcnt vmcnt(" #n ")" ::: "memory")
; #define PG8_WAIT_L(n) asm volatile("s_waitcnt lgkmcnt(" #n ")" ::: "memory")
; #define PG8_BAR __builtin_amdgcn_s_barrier()
; #define PG8_SCHED __builtin_amdgcn_sched_barrier(0)
; template <class Epi, class Sched, bool ALIGN_EPI = false, bool SP2 = false>
; __device__ __forceinline__ void gemm_phase(PG8_LAS unsigned char* lds, const Gemm g, const Sched& S, const Epi& E) {
;     ...
;             PG8_WAIT_V(8); PG8_WAIT_L(0); PG8_BAR; PG8_MMA(1, 0, At, B0); PG8_MMA(1, 1, At, B1); PG8_BAR; PG8_SCHED;
;             PG8_LDB(B0, 1, 0); PG8_LDB(B1, 1, 1); PG8_SCHED; PG8_LDA(At, 1, 0); PG8_STAGE(PG8_SA(0, 1), a2 + hstep, voffA);
;             PG8_WAIT_V(8); PG8_WAIT_L(0); PG8_BAR; PG8_MMA(0, 0, At, B0); PG8_MMA(0, 1, At, B1); PG8_BAR; PG8_SCHED;
	v_mfma_f32_16x16x32_bf16 v[60:63], v[150:153], v[196:199], 0
	v_mfma_f32_16x16x32_bf16 v[56:59], v[158:161], v[196:199], 0
	v_mfma_f32_16x16x32_bf16 v[48:51], v[150:153], v[212:215], 0
	v_mfma_f32_16x16x32_bf16 v[40:43], v[158:161], v[212:215], 0
	v_mfma_f32_16x16x32_bf16 v[32:35], v[150:153], v[220:223], 0
	v_mfma_f32_16x16x32_bf16 v[24:27], v[158:161], v[220:223], 0
	v_mfma_f32_16x16x32_bf16 v[16:19], v[150:153], v[228:231], 0
	v_mfma_f32_16x16x32_bf16 v[8:11], v[158:161], v[228:231], 0
	v_mfma_f32_16x16x32_bf16 v[60:63], v[154:157], v[208:211], v[60:63]
	v_mfma_f32_16x16x32_bf16 v[56:59], v[176:179], v[208:211], v[56:59]
	v_mfma_f32_16x16x32_bf16 v[48:51], v[154:157], v[216:219], v[48:51]
	v_mfma_f32_16x16x32_bf16 v[40:43], v[176:179], v[216:219], v[40:43]
	v_mfma_f32_16x16x32_bf16 v[32:35], v[154:157], v[224:227], v[32:35]
	v_mfma_f32_16x16x32_bf16 v[24:27], v[176:179], v[224:227], v[24:27]
	v_mfma_f32_16x16x32_bf16 v[16:19], v[154:157], v[232:235], v[16:19]
	v_mfma_f32_16x16x32_bf16 v[8:11], v[176:179], v[232:235], v[8:11]
	v_mfma_f32_16x16x32_bf16 v[52:55], v[180:183], v[196:199], 0
	v_mfma_f32_16x16x32_bf16 v[44:47], v[188:191], v[196:199], 0
	v_mfma_f32_16x16x32_bf16 v[36:39], v[180:183], v[212:215], 0
	v_mfma_f32_16x16x32_bf16 v[28:31], v[188:191], v[212:215], 0
	v_mfma_f32_16x16x32_bf16 v[20:23], v[180:183], v[220:223], 0
	v_mfma_f32_16x16x32_bf16 v[12:15], v[188:191], v[220:223], 0
	v_mfma_f32_16x16x32_bf16 v[4:7], v[180:183], v[228:231], 0
	v_mfma_f32_16x16x32_bf16 v[0:3], v[188:191], v[228:231], 0
	v_mfma_f32_16x16x32_bf16 v[52:55], v[184:187], v[208:211], v[52:55]
	v_mfma_f32_16x16x32_bf16 v[44:47], v[192:195], v[208:211], v[44:47]
	v_mfma_f32_16x16x32_bf16 v[36:39], v[184:187], v[216:219], v[36:39]
	v_mfma_f32_16x16x32_bf16 v[28:31], v[192:195], v[216:219], v[28:31]
	v_mfma_f32_16x16x32_bf16 v[20:23], v[184:187], v[224:227], v[20:23]
	v_mfma_f32_16x16x32_bf16 v[12:15], v[192:195], v[224:227], v[12:15]
	v_mfma_f32_16x16x32_bf16 v[4:7], v[184:187], v[232:235], v[4:7]
	v_mfma_f32_16x16x32_bf16 v[0:3], v[192:195], v[232:235], v[0:3]
	s_setprio 0
	s_barrier
	s_add_i32 s69, 0, 0x18000
	v_add_u32_e32 v144, s69, v148
	s_add_i32 s70, 0, 0x1c000
	ds_read_b128 v[150:153], v144
	ds_read_b128 v[154:157], v144 offset:1024
	ds_read_b128 v[158:161], v144 offset:2048
	ds_read_b128 v[176:179], v144 offset:3072
	v_add_u32_e32 v144, s70, v148
	ds_read_b128 v[180:183], v144
	ds_read_b128 v[184:187], v144 offset:1024
	ds_read_b128 v[188:191], v144 offset:2048
	ds_read_b128 v[192:195], v144 offset:3072
	s_add_u32 s50, s50, 0x40000
	s_addc_u32 s51, s51, 0
	s_mov_b32 m0, s55
	v_lshl_add_u64 v[238:239], s[50:51], 0, v[136:137]
	ds_read_b128 v[196:199], v149 offset:32768
	ds_read_b128 v[208:211], v149 offset:33792
	ds_read_b128 v[212:215], v149 offset:34816
	ds_read_b128 v[216:219], v149 offset:35840
	ds_read_b128 v[220:223], v149 offset:36864
	ds_read_b128 v[224:227], v149 offset:37888
	ds_read_b128 v[228:231], v149 offset:38912
	ds_read_b128 v[232:235], v149 offset:39936
	global_load_lds_dwordx4 v[238:239], off
	v_lshl_add_u64 v[238:239], s[50:51], 0, v[132:133]
	s_mov_b32 m0, s56
	s_nop 0
	global_load_lds_dwordx4 v[238:239], off
	s_waitcnt vmcnt(8)
	s_waitcnt lgkmcnt(0)
	s_setprio 1
	s_barrier
	v_mfma_f32_16x16x32_bf16 v[126:129], v[150:153], v[196:199], v[126:129]
	v_mfma_f32_16x16x32_bf16 v[122:125], v[158:161], v[196:199], v[122:125]
	v_mfma_f32_16x16x32_bf16 v[114:117], v[150:153], v[212:215], v[114:117]
	v_mfma_f32_16x16x32_bf16 v[106:109], v[158:161], v[212:215], v[106:109]
	v_mfma_f32_16x16x32_bf16 v[98:101], v[150:153], v[220:223], v[98:101]
	v_mfma_f32_16x16x32_bf16 v[90:93], v[158:161], v[220:223], v[90:93]
	v_mfma_f32_16x16x32_bf16 v[82:85], v[150:153], v[228:231], v[82:85]
	v_mfma_f32_16x16x32_bf16 v[72:75], v[158:161], v[228:231], v[72:75]
	v_mfma_f32_16x16x32_bf16 v[126:129], v[154:157], v[208:211], v[126:129]
	v_mfma_f32_16x16x32_bf16 v[122:125], v[176:179], v[208:211], v[122:125]
	v_mfma_f32_16x16x32_bf16 v[114:117], v[154:157], v[216:219], v[114:117]
	v_mfma_f32_16x16x32_bf16 v[106:109], v[176:179], v[216:219], v[106:109]
	v_mfma_f32_16x16x32_bf16 v[98:101], v[154:157], v[224:227], v[98:101]
	v_mfma_f32_16x16x32_bf16 v[90:93], v[176:179], v[224:227], v[90:93]
	v_mfma_f32_16x16x32_bf16 v[82:85], v[154:157], v[232:235], v[82:85]
	v_mfma_f32_16x16x32_bf16 v[72:75], v[176:179], v[232:235], v[72:75]
	v_mfma_f32_16x16x32_bf16 v[118:121], v[180:183], v[196:199], v[118:121]
	v_mfma_f32_16x16x32_bf16 v[110:113], v[188:191], v[196:199], v[110:113]
	v_mfma_f32_16x16x32_bf16 v[102:105], v[180:183], v[212:215], v[102:105]
	v_mfma_f32_16x16x32_bf16 v[94:97], v[188:191], v[212:215], v[94:97]
	v_mfma_f32_16x16x32_bf16 v[86:89], v[180:183], v[220:223], v[86:89]
	v_mfma_f32_16x16x32_bf16 v[76:79], v[188:191], v[220:223], v[76:79]
	v_mfma_f32_16x16x32_bf16 v[68:71], v[180:183], v[228:231], v[68:71]
	v_mfma_f32_16x16x32_bf16 v[64:67], v[188:191], v[228:231], v[64:67]
	v_mfma_f32_16x16x32_bf16 v[118:121], v[184:187], v[208:211], v[118:121]
	v_mfma_f32_16x16x32_bf16 v[110:113], v[192:195], v[208:211], v[110:113]
	v_mfma_f32_16x16x32_bf16 v[102:105], v[184:187], v[216:219], v[102:105]
	v_mfma_f32_16x16x32_bf16 v[94:97], v[192:195], v[216:219], v[94:97]
	v_mfma_f32_16x16x32_bf16 v[86:89], v[184:187], v[224:227], v[86:89]
	v_mfma_f32_16x16x32_bf16 v[76:79], v[192:195], v[224:227], v[76:79]
	v_mfma_f32_16x16x32_bf16 v[68:71], v[184:187], v[232:235], v[68:71]
	v_mfma_f32_16x16x32_bf16 v[64:67], v[192:195], v[232:235], v[64:67]
	s_setprio 0
	s_barrier
; #define PG8_STAGE(bufoff, gbase, voff) do { _Pragma("unroll") for (int _i = 0; _i < 2; ++_i) \
;         __builtin_amdgcn_global_load_lds((const unsigned*)((const char*)(gbase) + (voff)[_i]), (PG8_LAS unsigned*)(lds + (bufoff) + ldsw + _i * 8192), 16, 0, 0); } while (0)
; #define PG8_LDA(dst, b, h) do { _Pragma("unroll") for (int m = 0; m < 4; ++m) _Pragma("unroll") for (int k = 0; k < 2; ++k) dst[m][k] = *(const PG8_LAS bf16x8*)(lds + PG8_SA(b, h) + aoff + m * 2048 + k * 1024); } while (0)
; #define PG8_MMA(ai, bj, At, Bt) do { __builtin_amdgcn_s_setprio(1); _Pragma("unroll") for (int m = 0; m < 4; ++m) _Pragma("unroll") for (int n = 0; n < 2; ++n) _Pragma("unroll") for (int k = 0; k < 2; ++k) \
;         acc[ai][bj][m][n] = __builtin_amdgcn_mfma_f32_16x16x32_bf16(Bt[n][k], At[m][k], acc[ai][bj][m][n], 0, 0, 0); __builtin_amdgcn_s_setprio(0); } while (0)
; #define PG8_WAIT_V(n) asm volatile("s_waitcnt vmcnt(" #n ")" ::: "memory")
; #define PG8_WAIT_L(n) asm volatile("s_waitcnt lgkmcnt(" #n ")" ::: "memory")
; #define PG8_BAR __builtin_amdgcn_s_barrier()
; #define PG8_SCHED __builtin_amdgcn_sched_barrier(0)
; template <class Epi, class Sched, bool ALIGN_EPI = false, bool SP2 = false>
; __device__ __forceinline__ void gemm_phase(PG8_LAS unsigned char* lds, const Gemm g, const Sched& S, const Epi& E) {
;     ...
;             PG8_LDA(At, 1, 1); PG8_STAGE(PG8_SB(1, 0), b3, voffB); PG8_STAGE(PG8_SB(1, 1), b3 + hstep, voffB); PG8_STAGE(PG8_SA(1, 0), a3, voffA);
;             PG8_WAIT_V(8); PG8_WAIT_L(0); PG8_BAR; PG8_MMA(1, 0, At, B0); PG8_MMA(1, 1, At, B1); PG8_BAR; PG8_SCHED;
	s_add_i32 s50, s69, s52
	v_lshl_add_u64 v[142:143], v[142:143], 0, s[40:41]
	s_mov_b32 m0, s50
	ds_read_b128 v[196:199], v149 offset:49152
	ds_read_b128 v[208:211], v149 offset:50176
	ds_read_b128 v[212:215], v149 offset:51200
	ds_read_b128 v[216:219], v149 offset:52224
	ds_read_b128 v[220:223], v149 offset:53248
	ds_read_b128 v[224:227], v149 offset:54272
	ds_read_b128 v[228:231], v149 offset:55296
	ds_read_b128 v[232:235], v149 offset:56320
	global_load_lds_dwordx4 v[142:143], off
	s_add_i32 m0, s50, 0x2000
	s_add_u32 s48, s48, 0x40080
	v_lshl_add_u64 v[142:143], v[146:147], 0, s[40:41]
	s_addc_u32 s49, s49, 0
	s_add_i32 s50, s70, s52
	global_load_lds_dwordx4 v[142:143], off
	v_lshl_add_u64 v[142:143], s[48:49], 0, v[134:135]
	s_mov_b32 m0, s50
	s_nop 0
	global_load_lds_dwordx4 v[142:143], off
	v_lshl_add_u64 v[142:143], s[48:49], 0, v[130:131]
	s_add_i32 m0, s50, 0x2000
	s_nop 0
	global_load_lds_dwordx4 v[142:143], off
	v_lshl_add_u64 v[142:143], v[200:201], 0, s[40:41]
	s_mov_b32 m0, s59
	s_nop 0
	global_load_lds_dwordx4 v[142:143], off
	v_lshl_add_u64 v[142:143], v[236:237], 0, s[40:41]
	s_mov_b32 m0, s60
	s_nop 0
	global_load_lds_dwordx4 v[142:143], off
	s_waitcnt vmcnt(8)
	s_waitcnt lgkmcnt(0)
	s_setprio 1
	s_barrier
	v_mfma_f32_16x16x32_bf16 v[60:63], v[150:153], v[196:199], v[60:63]
	v_mfma_f32_16x16x32_bf16 v[56:59], v[158:161], v[196:199], v[56:59]
	v_mfma_f32_16x16x32_bf16 v[48:51], v[150:153], v[212:215], v[48:51]
	v_mfma_f32_16x16x32_bf16 v[40:43], v[158:161], v[212:215], v[40:43]
	v_mfma_f32_16x16x32_bf16 v[32:35], v[150:153], v[220:223], v[32:35]
	v_mfma_f32_16x16x32_bf16 v[24:27], v[158:161], v[220:223], v[24:27]
	v_mfma_f32_16x16x32_bf16 v[16:19], v[150:153], v[228:231], v[16:19]
	v_mfma_f32_16x16x32_bf16 v[8:11], v[158:161], v[228:231], v[8:11]
	v_mfma_f32_16x16x32_bf16 v[60:63], v[154:157], v[208:211], v[60:63]
	v_mfma_f32_16x16x32_bf16 v[56:59], v[176:179], v[208:211], v[56:59]
	v_mfma_f32_16x16x32_bf16 v[48:51], v[154:157], v[216:219], v[48:51]
	v_mfma_f32_16x16x32_bf16 v[40:43], v[176:179], v[216:219], v[40:43]
	v_mfma_f32_16x16x32_bf16 v[32:35], v[154:157], v[224:227], v[32:35]
	v_mfma_f32_16x16x32_bf16 v[24:27], v[176:179], v[224:227], v[24:27]
	v_mfma_f32_16x16x32_bf16 v[16:19], v[154:157], v[232:235], v[16:19]
	v_mfma_f32_16x16x32_bf16 v[8:11], v[176:179], v[232:235], v[8:11]
	v_mfma_f32_16x16x32_bf16 v[52:55], v[180:183], v[196:199], v[52:55]
	v_mfma_f32_16x16x32_bf16 v[44:47], v[188:191], v[196:199], v[44:47]
	v_mfma_f32_16x16x32_bf16 v[36:39], v[180:183], v[212:215], v[36:39]
	v_mfma_f32_16x16x32_bf16 v[28:31], v[188:191], v[212:215], v[28:31]
	v_mfma_f32_16x16x32_bf16 v[20:23], v[180:183], v[220:223], v[20:23]
	v_mfma_f32_16x16x32_bf16 v[12:15], v[188:191], v[220:223], v[12:15]
	v_mfma_f32_16x16x32_bf16 v[4:7], v[180:183], v[228:231], v[4:7]
	v_mfma_f32_16x16x32_bf16 v[0:3], v[188:191], v[228:231], v[0:3]
	v_mfma_f32_16x16x32_bf16 v[52:55], v[184:187], v[208:211], v[52:55]
	v_mfma_f32_16x16x32_bf16 v[44:47], v[192:195], v[208:211], v[44:47]
	v_mfma_f32_16x16x32_bf16 v[36:39], v[184:187], v[216:219], v[36:39]
	v_mfma_f32_16x16x32_bf16 v[28:31], v[192:195], v[216:219], v[28:31]
	v_mfma_f32_16x16x32_bf16 v[20:23], v[184:187], v[224:227], v[20:23]
	v_mfma_f32_16x16x32_bf16 v[12:15], v[192:195], v[224:227], v[12:15]
	v_mfma_f32_16x16x32_bf16 v[4:7], v[184:187], v[232:235], v[4:7]
	v_mfma_f32_16x16x32_bf16 v[0:3], v[192:195], v[232:235], v[0:3]
	s_setprio 0
	s_barrier
	s_add_i32 s68, s68, 2
	s_add_u32 s46, s46, 0x100
	s_addc_u32 s47, s47, 0
	s_add_u32 s66, s66, 0x100
	s_addc_u32 s67, s67, 0
	s_cmp_gt_u32 s68, 13
	s_cbranch_scc1 .Lpeel_exit_1

; #define PG8_STAGE(bufoff, gbase, voff) do { _Pragma("unroll") for (int _i = 0; _i < 2; ++_i) \
;         __builtin_amdgcn_global_load_lds((const unsigned*)((const char*)(gbase) + (voff)[_i]), (PG8_LAS unsigned*)(lds + (bufoff) + ldsw + _i * 8192), 16, 0, 0); } while (0)
; #define PG8_LDA(dst, b, h) do { _Pragma("unroll") for (int m = 0; m < 4; ++m) _Pragma("unroll") for (int k = 0; k < 2; ++k) dst[m][k] = *(const PG8_LAS bf16x8*)(lds + PG8_SA(b, h) + aoff + m * 2048 + k * 1024); } while (0)
; #define PG8_LDB(dst, b, h) do { _Pragma("unroll") for (int n = 0; n < 2; ++n) _Pragma("unroll") for (int k = 0; k < 2; ++k) dst[n][k] = *(const PG8_LAS bf16x8*)(lds + PG8_SB(b, h) + boff + n * 2048 + k * 1024); } while (0)
; #define PG8_WAIT_V(n) asm volatile("s_waitcnt vmcnt(" #n ")" ::: "memory")
; #define PG8_BAR __builtin_amdgcn_s_barrier()
; template <class Epi, class Sched, bool ALIGN_EPI = false, bool SP2 = false>
; __device__ __forceinline__ void gemm_phase(PG8_LAS unsigned char* lds, const Gemm g, const Sched& S, const Epi& E) {
;     ...
;         const bool has_next = S.next(ui + 1, nxt);
;         const char* nA = has_next ? (const char*)(nxt.sw ? g.A2 : g.A) + (size_t)nxt.pm * tstep : cA; const char* nB = has_next ? (const char*)(nxt.sw ? g.Bt2 : g.Bt) + (size_t)nxt.pn * tstep : cB;
;         for (int t = 0; t < nt; t += 2) {
;             if constexpr (Epi::PF_TRIPS > 0) { if (t == nt - 2 * Epi::PF_TRIPS) E.prefetch(cur, tid, lds + STAGE_BYTES + wid * 512); }
;             const bool last = (t == nt - 2);
;             const char* a1 = cA + (size_t)(t + 1) * kstep;
;             const char* a2 = last ? nA : cA + (size_t)(t + 2) * kstep; const char* b2 = last ? nB : cB + (size_t)(t + 2) * kstep;
;             const char* a3 = a2 + kstep; const char* b3 = b2 + kstep;
;             if (last && has_next) S.a_ready(nxt);
;             if constexpr (SP2) {
;             PG8_LDB(B0, 0, 0); PG8_LDB(B1, 0, 1); PG8_SCHED; PG8_LDA(At, 0, 0); PG8_STAGE(PG8_SA(1, 1), a1 + hstep, voffA);
;             PG8_WAIT_V(8); PG8_WAIT_L(0); PG8_BAR; PG8_MMA(0, 0, At, B0); PG8_MMA(0, 1, At, B1); PG8_BAR; PG8_SCHED;
;             PG8_LDA(At, 0, 1); PG8_STAGE(PG8_SB(0, 0), b2, voffB); PG8_STAGE(PG8_SB(0, 1), b2 + hstep, voffB); PG8_STAGE(PG8_SA(0, 0), a2, voffA);
;             PG8_WAIT_V(8); PG8_WAIT_L(0); PG8_BAR; PG8_MMA(1, 0, At, B0); PG8_MMA(1, 1, At, B1); PG8_BAR; PG8_SCHED;
.LBB0_158:
	s_ashr_i32 s17, s16, 31
	s_lshl_b64 s[44:45], s[16:17], 19
	s_cmp_eq_u32 s65, 0
	s_cselect_b32 s17, s30, s52
	s_cselect_b32 s5, s31, s53
	s_cselect_b32 s50, s38, s30
	s_cselect_b32 s51, s39, s31
	s_add_u32 s44, s17, s44
	s_addc_u32 s45, s5, s45
	s_and_b64 s[46:47], s[42:43], exec
	s_cselect_b32 s5, s45, s7
	s_cselect_b32 s17, s44, s6
	s_ashr_i32 s19, s18, 31
	s_lshl_b64 s[46:47], s[18:19], 19
	s_add_u32 s46, s50, s46
	s_addc_u32 s47, s51, s47
	s_and_b64 s[50:51], s[42:43], exec
	s_cselect_b32 s19, s47, s49
	s_cselect_b32 s67, s46, s48
	s_add_u32 s6, s6, 0x40080
	s_addc_u32 s7, s7, 0
	s_add_u32 s68, s48, 0x100
	s_addc_u32 s69, s49, 0
	s_mov_b32 s70, -2
	s_add_u32 s48, s6, 0xfffc0080
	s_addc_u32 s49, s7, -1
	s_add_i32 s71, 0, 0x10000
	s_cmp_eq_u32 s70, 12
	s_cselect_b32 s51, s5, s49
	s_cselect_b32 s50, s17, s48
	s_cselect_b32 s49, s19, s69
	s_cselect_b32 s48, s67, s68
	s_add_i32 s74, 0, 0x14000
	v_add_u32_e32 v142, s71, v199
	v_add_u32_e32 v158, s74, v199
	ds_read_b128 v[130:133], v142
	ds_read_b128 v[134:137], v142 offset:1024
	ds_read_b128 v[138:141], v142 offset:2048
	s_waitcnt lgkmcnt(0)
	ds_read_b128 v[142:145], v142 offset:3072
	ds_read_b128 v[146:149], v158
	ds_read_b128 v[150:153], v158 offset:1024
	ds_read_b128 v[154:157], v158 offset:2048
	ds_read_b128 v[158:161], v158 offset:3072
	v_lshl_add_u64 v[196:197], s[6:7], 0, v[184:185]
	s_add_i32 m0, s11, 0xc000
	ds_read_b128 v[188:191], v200
	ds_read_b128 v[192:195], v200 offset:1024
	ds_read_b128 v[208:211], v200 offset:2048
	ds_read_b128 v[212:215], v200 offset:3072
	ds_read_b128 v[216:219], v200 offset:4096
	ds_read_b128 v[220:223], v200 offset:5120
	ds_read_b128 v[224:227], v200 offset:6144
	ds_read_b128 v[228:231], v200 offset:7168
	global_load_lds_dwordx4 v[196:197], off
	v_lshl_add_u64 v[196:197], s[6:7], 0, v[186:187]
	s_add_i32 m0, s11, 0xe000
	s_nop 0
	global_load_lds_dwordx4 v[196:197], off
	s_waitcnt vmcnt(8)
	s_waitcnt lgkmcnt(0)
	s_setprio 1
	s_barrier
	v_mfma_f32_16x16x32_bf16 v[126:129], v[130:133], v[188:191], 0
	v_mfma_f32_16x16x32_bf16 v[122:125], v[138:141], v[188:191], 0
	v_mfma_f32_16x16x32_bf16 v[110:113], v[130:133], v[208:211], 0
	v_mfma_f32_16x16x32_bf16 v[106:109], v[138:141], v[208:211], 0
	v_mfma_f32_16x16x32_bf16 v[94:97], v[130:133], v[216:219], 0
	v_mfma_f32_16x16x32_bf16 v[90:93], v[138:141], v[216:219], 0
	v_mfma_f32_16x16x32_bf16 v[76:79], v[130:133], v[224:227], 0
	v_mfma_f32_16x16x32_bf16 v[72:75], v[138:141], v[224:227], 0
	v_mfma_f32_16x16x32_bf16 v[126:129], v[134:137], v[192:195], v[126:129]
	v_mfma_f32_16x16x32_bf16 v[122:125], v[142:145], v[192:195], v[122:125]
	v_mfma_f32_16x16x32_bf16 v[110:113], v[134:137], v[212:215], v[110:113]
	v_mfma_f32_16x16x32_bf16 v[106:109], v[142:145], v[212:215], v[106:109]
	v_mfma_f32_16x16x32_bf16 v[94:97], v[134:137], v[220:223], v[94:97]
	v_mfma_f32_16x16x32_bf16 v[90:93], v[142:145], v[220:223], v[90:93]
	v_mfma_f32_16x16x32_bf16 v[76:79], v[134:137], v[228:231], v[76:79]
	v_mfma_f32_16x16x32_bf16 v[72:75], v[142:145], v[228:231], v[72:75]
	v_mfma_f32_16x16x32_bf16 v[118:121], v[146:149], v[188:191], 0
	v_mfma_f32_16x16x32_bf16 v[114:117], v[154:157], v[188:191], 0
	v_mfma_f32_16x16x32_bf16 v[102:105], v[146:149], v[208:211], 0
	v_mfma_f32_16x16x32_bf16 v[98:101], v[154:157], v[208:211], 0
	v_mfma_f32_16x16x32_bf16 v[86:89], v[146:149], v[216:219], 0
	v_mfma_f32_16x16x32_bf16 v[82:85], v[154:157], v[216:219], 0
	v_mfma_f32_16x16x32_bf16 v[68:71], v[146:149], v[224:227], 0
	v_mfma_f32_16x16x32_bf16 v[64:67], v[154:157], v[224:227], 0
	v_mfma_f32_16x16x32_bf16 v[118:121], v[150:153], v[192:195], v[118:121]
	v_mfma_f32_16x16x32_bf16 v[114:117], v[158:161], v[192:195], v[114:117]
	v_mfma_f32_16x16x32_bf16 v[102:105], v[150:153], v[212:215], v[102:105]
	v_mfma_f32_16x16x32_bf16 v[98:101], v[158:161], v[212:215], v[98:101]
	v_mfma_f32_16x16x32_bf16 v[86:89], v[150:153], v[220:223], v[86:89]
	v_mfma_f32_16x16x32_bf16 v[82:85], v[158:161], v[220:223], v[82:85]
	v_mfma_f32_16x16x32_bf16 v[68:71], v[150:153], v[228:231], v[68:71]
	v_mfma_f32_16x16x32_bf16 v[64:67], v[158:161], v[228:231], v[64:67]
	s_setprio 0
	s_barrier
	s_add_i32 s71, s71, s54
	v_lshl_add_u64 v[196:197], s[48:49], 0, v[178:179]
	s_mov_b32 m0, s71
	ds_read_b128 v[188:191], v200 offset:16384
	ds_read_b128 v[192:195], v200 offset:17408
	ds_read_b128 v[208:211], v200 offset:18432
	ds_read_b128 v[212:215], v200 offset:19456
	ds_read_b128 v[216:219], v200 offset:20480
	ds_read_b128 v[220:223], v200 offset:21504
	ds_read_b128 v[224:227], v200 offset:22528
	ds_read_b128 v[228:231], v200 offset:23552
	global_load_lds_dwordx4 v[196:197], off
	s_add_i32 m0, s71, 0x2000
	s_add_u32 s72, s48, 0x40000
	v_lshl_add_u64 v[232:233], s[48:49], 0, v[182:183]
	s_addc_u32 s73, s49, 0
	s_add_i32 s71, s74, s54
	global_load_lds_dwordx4 v[232:233], off
	v_lshl_add_u64 v[234:235], s[72:73], 0, v[178:179]
	s_mov_b32 m0, s71
	v_lshl_add_u64 v[236:237], s[50:51], 0, v[180:181]
	global_load_lds_dwordx4 v[234:235], off
	v_lshl_add_u64 v[234:235], s[72:73], 0, v[182:183]
	s_add_i32 m0, s71, 0x2000
	s_nop 0
	global_load_lds_dwordx4 v[234:235], off
	v_lshl_add_u64 v[234:235], s[50:51], 0, v[176:177]
	s_mov_b32 m0, s11
	s_nop 0
	global_load_lds_dwordx4 v[234:235], off
	s_mov_b32 m0, s55
	s_nop 0
	global_load_lds_dwordx4 v[236:237], off
	s_waitcnt vmcnt(8)
	s_waitcnt lgkmcnt(0)
	s_setprio 1
	s_barrier
; #define PG8_STAGE(bufoff, gbase, voff) do { _Pragma("unroll") for (int _i = 0; _i < 2; ++_i) \
;         __builtin_amdgcn_global_load_lds((const unsigned*)((const char*)(gbase) + (voff)[_i]), (PG8_LAS unsigned*)(lds + (bufoff) + ldsw + _i * 8192), 16, 0, 0); } while (0)
; #define PG8_LDA(dst, b, h) do { _Pragma("unroll") for (int m = 0; m < 4; ++m) _Pragma("unroll") for (int k = 0; k < 2; ++k) dst[m][k] = *(const PG8_LAS bf16x8*)(lds + PG8_SA(b, h) + aoff + m * 2048 + k * 1024); } while (0)
; #define PG8_LDB(dst, b, h) do { _Pragma("unroll") for (int n = 0; n < 2; ++n) _Pragma("unroll") for (int k = 0; k < 2; ++k) dst[n][k] = *(const PG8_LAS bf16x8*)(lds + PG8_SB(b, h) + boff + n * 2048 + k * 1024); } while (0)
; #define PG8_MMA(ai, bj, At, Bt) do { __builtin_amdgcn_s_setprio(1); _Pragma("unroll") for (int m = 0; m < 4; ++m) _Pragma("unroll") for (int n = 0; n < 2; ++n) _Pragma("unroll") for (int k = 0; k < 2; ++k) \
;         acc[ai][bj][m][n] = __builtin_amdgcn_mfma_f32_16x16x32_bf16(Bt[n][k], At[m][k], acc[ai][bj][m][n], 0, 0, 0); __builtin_amdgcn_s_setprio(0); } while (0)
; #define PG8_WAIT_V(n) asm volatile("s_waitcnt vmcnt(" #n ")" ::: "memory")
; #define PG8_WAIT_L(n) asm volatile("s_waitcnt lgkmcnt(" #n ")" ::: "memory")
; #define PG8_BAR __builtin_amdgcn_s_barrier()
; #define PG8_SCHED __builtin_amdgcn_sched_barrier(0)
; template <class Epi, class Sched, bool ALIGN_EPI = false, bool SP2 = false>
; __device__ __forceinline__ void gemm_phase(PG8_LAS unsigned char* lds, const Gemm g, const Sched& S, const Epi& E) {
;     ...
;             PG8_WAIT_V(8); PG8_WAIT_L(0); PG8_BAR; PG8_MMA(1, 0, At, B0); PG8_MMA(1, 1, At, B1); PG8_BAR; PG8_SCHED;
;             PG8_LDB(B0, 1, 0); PG8_LDB(B1, 1, 1); PG8_SCHED; PG8_LDA(At, 1, 0); PG8_STAGE(PG8_SA(0, 1), a2 + hstep, voffA);
;             PG8_WAIT_V(8); PG8_WAIT_L(0); PG8_BAR; PG8_MMA(0, 0, At, B0); PG8_MMA(0, 1, At, B1); PG8_BAR; PG8_SCHED;
	v_mfma_f32_16x16x32_bf16 v[60:63], v[130:133], v[188:191], 0
	v_mfma_f32_16x16x32_bf16 v[56:59], v[138:141], v[188:191], 0
	v_mfma_f32_16x16x32_bf16 v[44:47], v[130:133], v[208:211], 0
	v_mfma_f32_16x16x32_bf16 v[40:43], v[138:141], v[208:211], 0
	v_mfma_f32_16x16x32_bf16 v[28:31], v[130:133], v[216:219], 0
	v_mfma_f32_16x16x32_bf16 v[24:27], v[138:141], v[216:219], 0
	v_mfma_f32_16x16x32_bf16 v[12:15], v[130:133], v[224:227], 0
	v_mfma_f32_16x16x32_bf16 v[8:11], v[138:141], v[224:227], 0
	v_mfma_f32_16x16x32_bf16 v[60:63], v[134:137], v[192:195], v[60:63]
	v_mfma_f32_16x16x32_bf16 v[56:59], v[142:145], v[192:195], v[56:59]
	v_mfma_f32_16x16x32_bf16 v[44:47], v[134:137], v[212:215], v[44:47]
	v_mfma_f32_16x16x32_bf16 v[40:43], v[142:145], v[212:215], v[40:43]
	v_mfma_f32_16x16x32_bf16 v[28:31], v[134:137], v[220:223], v[28:31]
	v_mfma_f32_16x16x32_bf16 v[24:27], v[142:145], v[220:223], v[24:27]
	v_mfma_f32_16x16x32_bf16 v[12:15], v[134:137], v[228:231], v[12:15]
	v_mfma_f32_16x16x32_bf16 v[8:11], v[142:145], v[228:231], v[8:11]
	v_mfma_f32_16x16x32_bf16 v[52:55], v[146:149], v[188:191], 0
	v_mfma_f32_16x16x32_bf16 v[48:51], v[154:157], v[188:191], 0
	v_mfma_f32_16x16x32_bf16 v[36:39], v[146:149], v[208:211], 0
	v_mfma_f32_16x16x32_bf16 v[32:35], v[154:157], v[208:211], 0
	v_mfma_f32_16x16x32_bf16 v[20:23], v[146:149], v[216:219], 0
	v_mfma_f32_16x16x32_bf16 v[16:19], v[154:157], v[216:219], 0
	v_mfma_f32_16x16x32_bf16 v[4:7], v[146:149], v[224:227], 0
	v_mfma_f32_16x16x32_bf16 v[0:3], v[154:157], v[224:227], 0
	v_mfma_f32_16x16x32_bf16 v[52:55], v[150:153], v[192:195], v[52:55]
	v_mfma_f32_16x16x32_bf16 v[48:51], v[158:161], v[192:195], v[48:51]
	v_mfma_f32_16x16x32_bf16 v[36:39], v[150:153], v[212:215], v[36:39]
	v_mfma_f32_16x16x32_bf16 v[32:35], v[158:161], v[212:215], v[32:35]
	v_mfma_f32_16x16x32_bf16 v[20:23], v[150:153], v[220:223], v[20:23]
	v_mfma_f32_16x16x32_bf16 v[16:19], v[158:161], v[220:223], v[16:19]
	v_mfma_f32_16x16x32_bf16 v[4:7], v[150:153], v[228:231], v[4:7]
	v_mfma_f32_16x16x32_bf16 v[0:3], v[158:161], v[228:231], v[0:3]
	s_setprio 0
	s_barrier
	s_add_i32 s71, 0, 0x18000
	s_add_i32 s72, 0, 0x1c000
	v_add_u32_e32 v142, s71, v199
	v_add_u32_e32 v158, s72, v199
	ds_read_b128 v[130:133], v142
	ds_read_b128 v[134:137], v142 offset:1024
	ds_read_b128 v[138:141], v142 offset:2048
	ds_read_b128 v[142:145], v142 offset:3072
	ds_read_b128 v[146:149], v158
	ds_read_b128 v[150:153], v158 offset:1024
	ds_read_b128 v[154:157], v158 offset:2048
	ds_read_b128 v[158:161], v158 offset:3072
	s_add_u32 s50, s50, 0x40000
	s_addc_u32 s51, s51, 0
	s_mov_b32 m0, s56
	v_lshl_add_u64 v[238:239], s[50:51], 0, v[176:177]
	ds_read_b128 v[188:191], v200 offset:32768
	ds_read_b128 v[192:195], v200 offset:33792
	ds_read_b128 v[208:211], v200 offset:34816
	ds_read_b128 v[212:215], v200 offset:35840
	ds_read_b128 v[216:219], v200 offset:36864
	ds_read_b128 v[220:223], v200 offset:37888
	ds_read_b128 v[224:227], v200 offset:38912
	ds_read_b128 v[228:231], v200 offset:39936
	global_load_lds_dwordx4 v[238:239], off
	v_lshl_add_u64 v[238:239], s[50:51], 0, v[180:181]
	s_mov_b32 m0, s57
	s_nop 0
	global_load_lds_dwordx4 v[238:239], off
	s_waitcnt vmcnt(8)
	s_waitcnt lgkmcnt(0)
	s_setprio 1
	s_barrier
	v_mfma_f32_16x16x32_bf16 v[126:129], v[130:133], v[188:191], v[126:129]
	v_mfma_f32_16x16x32_bf16 v[122:125], v[138:141], v[188:191], v[122:125]
	v_mfma_f32_16x16x32_bf16 v[110:113], v[130:133], v[208:211], v[110:113]
	v_mfma_f32_16x16x32_bf16 v[106:109], v[138:141], v[208:211], v[106:109]
	v_mfma_f32_16x16x32_bf16 v[94:97], v[130:133], v[216:219], v[94:97]
	v_mfma_f32_16x16x32_bf16 v[90:93], v[138:141], v[216:219], v[90:93]
	v_mfma_f32_16x16x32_bf16 v[76:79], v[130:133], v[224:227], v[76:79]
	v_mfma_f32_16x16x32_bf16 v[72:75], v[138:141], v[224:227], v[72:75]
	v_mfma_f32_16x16x32_bf16 v[126:129], v[134:137], v[192:195], v[126:129]
	v_mfma_f32_16x16x32_bf16 v[122:125], v[142:145], v[192:195], v[122:125]
	v_mfma_f32_16x16x32_bf16 v[110:113], v[134:137], v[212:215], v[110:113]
	v_mfma_f32_16x16x32_bf16 v[106:109], v[142:145], v[212:215], v[106:109]
	v_mfma_f32_16x16x32_bf16 v[94:97], v[134:137], v[220:223], v[94:97]
	v_mfma_f32_16x16x32_bf16 v[90:93], v[142:145], v[220:223], v[90:93]
	v_mfma_f32_16x16x32_bf16 v[76:79], v[134:137], v[228:231], v[76:79]
	v_mfma_f32_16x16x32_bf16 v[72:75], v[142:145], v[228:231], v[72:75]
	v_mfma_f32_16x16x32_bf16 v[118:121], v[146:149], v[188:191], v[118:121]
	v_mfma_f32_16x16x32_bf16 v[114:117], v[154:157], v[188:191], v[114:117]
	v_mfma_f32_16x16x32_bf16 v[102:105], v[146:149], v[208:211], v[102:105]
	v_mfma_f32_16x16x32_bf16 v[98:101], v[154:157], v[208:211], v[98:101]
	v_mfma_f32_16x16x32_bf16 v[86:89], v[146:149], v[216:219], v[86:89]
	v_mfma_f32_16x16x32_bf16 v[82:85], v[154:157], v[216:219], v[82:85]
	v_mfma_f32_16x16x32_bf16 v[68:71], v[146:149], v[224:227], v[68:71]
	v_mfma_f32_16x16x32_bf16 v[64:67], v[154:157], v[224:227], v[64:67]
	v_mfma_f32_16x16x32_bf16 v[118:121], v[150:153], v[192:195], v[118:121]
	v_mfma_f32_16x16x32_bf16 v[114:117], v[158:161], v[192:195], v[114:117]
	v_mfma_f32_16x16x32_bf16 v[102:105], v[150:153], v[212:215], v[102:105]
	v_mfma_f32_16x16x32_bf16 v[98:101], v[158:161], v[212:215], v[98:101]
	v_mfma_f32_16x16x32_bf16 v[86:89], v[150:153], v[220:223], v[86:89]
	v_mfma_f32_16x16x32_bf16 v[82:85], v[158:161], v[220:223], v[82:85]
	v_mfma_f32_16x16x32_bf16 v[68:71], v[150:153], v[228:231], v[68:71]
	v_mfma_f32_16x16x32_bf16 v[64:67], v[158:161], v[228:231], v[64:67]
	s_setprio 0
	s_barrier
; #define PG8_STAGE(bufoff, gbase, voff) do { _Pragma("unroll") for (int _i = 0; _i < 2; ++_i) \
;         __builtin_amdgcn_global_load_lds((const unsigned*)((const char*)(gbase) + (voff)[_i]), (PG8_LAS unsigned*)(lds + (bufoff) + ldsw + _i * 8192), 16, 0, 0); } while (0)
; #define PG8_LDA(dst, b, h) do { _Pragma("unroll") for (int m = 0; m < 4; ++m) _Pragma("unroll") for (int k = 0; k < 2; ++k) dst[m][k] = *(const PG8_LAS bf16x8*)(lds + PG8_SA(b, h) + aoff + m * 2048 + k * 1024); } while (0)
; #define PG8_MMA(ai, bj, At, Bt) do { __builtin_amdgcn_s_setprio(1); _Pragma("unroll") for (int m = 0; m < 4; ++m) _Pragma("unroll") for (int n = 0; n < 2; ++n) _Pragma("unroll") for (int k = 0; k < 2; ++k) \
;         acc[ai][bj][m][n] = __builtin_amdgcn_mfma_f32_16x16x32_bf16(Bt[n][k], At[m][k], acc[ai][bj][m][n], 0, 0, 0); __builtin_amdgcn_s_setprio(0); } while (0)
; #define PG8_WAIT_V(n) asm volatile("s_waitcnt vmcnt(" #n ")" ::: "memory")
; #define PG8_WAIT_L(n) asm volatile("s_waitcnt lgkmcnt(" #n ")" ::: "memory")
; #define PG8_BAR __builtin_amdgcn_s_barrier()
; #define PG8_SCHED __builtin_amdgcn_sched_barrier(0)
; template <class Epi, class Sched, bool ALIGN_EPI = false, bool SP2 = false>
; __device__ __forceinline__ void gemm_phase(PG8_LAS unsigned char* lds, const Gemm g, const Sched& S, const Epi& E) {
;     ...
;             PG8_LDA(At, 1, 1); PG8_STAGE(PG8_SB(1, 0), b3, voffB); PG8_STAGE(PG8_SB(1, 1), b3 + hstep, voffB); PG8_STAGE(PG8_SA(1, 0), a3, voffA);
;             PG8_WAIT_V(8); PG8_WAIT_L(0); PG8_BAR; PG8_MMA(1, 0, At, B0); PG8_MMA(1, 1, At, B1); PG8_BAR; PG8_SCHED;
	s_add_i32 s50, s71, s54
	v_lshl_add_u64 v[196:197], v[196:197], 0, s[40:41]
	s_mov_b32 m0, s50
	ds_read_b128 v[188:191], v200 offset:49152
	ds_read_b128 v[192:195], v200 offset:50176
	ds_read_b128 v[208:211], v200 offset:51200
	ds_read_b128 v[212:215], v200 offset:52224
	ds_read_b128 v[216:219], v200 offset:53248
	ds_read_b128 v[220:223], v200 offset:54272
	ds_read_b128 v[224:227], v200 offset:55296
	ds_read_b128 v[228:231], v200 offset:56320
	global_load_lds_dwordx4 v[196:197], off
	s_add_i32 m0, s50, 0x2000
	s_add_u32 s48, s48, 0x40080
	v_lshl_add_u64 v[196:197], v[232:233], 0, s[40:41]
	s_addc_u32 s49, s49, 0
	s_add_i32 s50, s72, s54
	global_load_lds_dwordx4 v[196:197], off
	v_lshl_add_u64 v[196:197], s[48:49], 0, v[178:179]
	s_mov_b32 m0, s50
	s_nop 0
	global_load_lds_dwordx4 v[196:197], off
	v_lshl_add_u64 v[196:197], s[48:49], 0, v[182:183]
	s_add_i32 m0, s50, 0x2000
	s_nop 0
	global_load_lds_dwordx4 v[196:197], off
	v_lshl_add_u64 v[196:197], v[234:235], 0, s[40:41]
	s_mov_b32 m0, s61
	s_nop 0
	global_load_lds_dwordx4 v[196:197], off
	v_lshl_add_u64 v[196:197], v[236:237], 0, s[40:41]
	s_mov_b32 m0, s62
	s_nop 0
	global_load_lds_dwordx4 v[196:197], off
	s_waitcnt vmcnt(8)
	s_waitcnt lgkmcnt(0)
	s_setprio 1
	s_barrier
	v_mfma_f32_16x16x32_bf16 v[60:63], v[130:133], v[188:191], v[60:63]
	v_mfma_f32_16x16x32_bf16 v[56:59], v[138:141], v[188:191], v[56:59]
	v_mfma_f32_16x16x32_bf16 v[44:47], v[130:133], v[208:211], v[44:47]
	v_mfma_f32_16x16x32_bf16 v[40:43], v[138:141], v[208:211], v[40:43]
	v_mfma_f32_16x16x32_bf16 v[28:31], v[130:133], v[216:219], v[28:31]
	v_mfma_f32_16x16x32_bf16 v[24:27], v[138:141], v[216:219], v[24:27]
	v_mfma_f32_16x16x32_bf16 v[12:15], v[130:133], v[224:227], v[12:15]
	v_mfma_f32_16x16x32_bf16 v[8:11], v[138:141], v[224:227], v[8:11]
	v_mfma_f32_16x16x32_bf16 v[60:63], v[134:137], v[192:195], v[60:63]
	v_mfma_f32_16x16x32_bf16 v[56:59], v[142:145], v[192:195], v[56:59]
	v_mfma_f32_16x16x32_bf16 v[44:47], v[134:137], v[212:215], v[44:47]
	v_mfma_f32_16x16x32_bf16 v[40:43], v[142:145], v[212:215], v[40:43]
	v_mfma_f32_16x16x32_bf16 v[28:31], v[134:137], v[220:223], v[28:31]
	v_mfma_f32_16x16x32_bf16 v[24:27], v[142:145], v[220:223], v[24:27]
	v_mfma_f32_16x16x32_bf16 v[12:15], v[134:137], v[228:231], v[12:15]
	v_mfma_f32_16x16x32_bf16 v[8:11], v[142:145], v[228:231], v[8:11]
	v_mfma_f32_16x16x32_bf16 v[52:55], v[146:149], v[188:191], v[52:55]
	v_mfma_f32_16x16x32_bf16 v[48:51], v[154:157], v[188:191], v[48:51]
	v_mfma_f32_16x16x32_bf16 v[36:39], v[146:149], v[208:211], v[36:39]
	v_mfma_f32_16x16x32_bf16 v[32:35], v[154:157], v[208:211], v[32:35]
	v_mfma_f32_16x16x32_bf16 v[20:23], v[146:149], v[216:219], v[20:23]
	v_mfma_f32_16x16x32_bf16 v[16:19], v[154:157], v[216:219], v[16:19]
	v_mfma_f32_16x16x32_bf16 v[4:7], v[146:149], v[224:227], v[4:7]
	v_mfma_f32_16x16x32_bf16 v[0:3], v[154:157], v[224:227], v[0:3]
	v_mfma_f32_16x16x32_bf16 v[52:55], v[150:153], v[192:195], v[52:55]
	v_mfma_f32_16x16x32_bf16 v[48:51], v[158:161], v[192:195], v[48:51]
	v_mfma_f32_16x16x32_bf16 v[36:39], v[150:153], v[212:215], v[36:39]
	v_mfma_f32_16x16x32_bf16 v[32:35], v[158:161], v[212:215], v[32:35]
	v_mfma_f32_16x16x32_bf16 v[20:23], v[150:153], v[220:223], v[20:23]
	v_mfma_f32_16x16x32_bf16 v[16:19], v[158:161], v[220:223], v[16:19]
	v_mfma_f32_16x16x32_bf16 v[4:7], v[150:153], v[228:231], v[4:7]
	v_mfma_f32_16x16x32_bf16 v[0:3], v[158:161], v[228:231], v[0:3]
	s_setprio 0
	s_barrier
	s_add_i32 s70, s70, 2
	s_add_u32 s6, s6, 0x100
	s_addc_u32 s7, s7, 0
	s_add_u32 s68, s68, 0x100
	s_addc_u32 s69, s69, 0
	s_cmp_gt_u32 s70, 13
	s_cbranch_scc1 .Lpeel_exit_2

; #define PG8_STAGE(bufoff, gbase, voff) do { _Pragma("unroll") for (int _i = 0; _i < 2; ++_i) \
;         __builtin_amdgcn_global_load_lds((const unsigned*)((const char*)(gbase) + (voff)[_i]), (PG8_LAS unsigned*)(lds + (bufoff) + ldsw + _i * 8192), 16, 0, 0); } while (0)
; #define PG8_WAIT_V(n) asm volatile("s_waitcnt vmcnt(" #n ")" ::: "memory")
; #define PG8_WAIT_L(n) asm volatile("s_waitcnt lgkmcnt(" #n ")" ::: "memory")
; template <class Epi, class Sched, bool ALIGN_EPI = false, bool SP2 = false>
; __device__ __forceinline__ void gemm_phase(PG8_LAS unsigned char* lds, const Gemm g, const Sched& S, const Epi& E) {
;     ...
;         for (int t = 0; t < nt; t += 2) {
;             if constexpr (Epi::PF_TRIPS > 0) { if (t == nt - 2 * Epi::PF_TRIPS) E.prefetch(cur, tid, lds + STAGE_BYTES + wid * 512); }
;             const bool last = (t == nt - 2);
;             const char* a1 = cA + (size_t)(t + 1) * kstep;
;             const char* a2 = last ? nA : cA + (size_t)(t + 2) * kstep; const char* b2 = last ? nB : cB + (size_t)(t + 2) * kstep;
;             const char* a3 = a2 + kstep; const char* b3 = b2 + kstep;
;             if (last && has_next) S.a_ready(nxt);
;             if constexpr (SP2) {
;             PG8_LDB(B0, 0, 0); PG8_LDB(B1, 0, 1); PG8_SCHED; PG8_LDA(At, 0, 0); PG8_STAGE(PG8_SA(1, 1), a1 + hstep, voffA);
;             PG8_WAIT_V(8); PG8_WAIT_L(0); PG8_BAR; PG8_MMA(0, 0, At, B0); PG8_MMA(0, 1, At, B1); PG8_BAR; PG8_SCHED;
;             PG8_LDA(At, 0, 1); PG8_STAGE(PG8_SB(0, 0), b2, voffB); PG8_STAGE(PG8_SB(0, 1), b2 + hstep, voffB); PG8_STAGE(PG8_SA(0, 0), a2, voffA);
;     __device__ __forceinline__ void prefetch(const Unit& u, int tid, PG8_LAS unsigned char* scratch) const {
;         const bf16_t* sb = xb + ((size_t)(u.pm * BM) * 1024 + u.pn * BM);
;         const unsigned voff = (unsigned)(((tid >> 2) * 1024 + (tid & 3) * 64) * 2);
;         const unsigned l0 = (unsigned)__builtin_amdgcn_readfirstlane((int)(unsigned)(uintptr_t)scratch);
;         const bf16_t* sb2 = sb + (size_t)128 * 1024;
;         unsigned keep;
;         asm volatile("s_mov_b32 %0, m0\n\ts_mov_b32 m0, %3\n\ts_nop 0\n\tglobal_load_lds_dword %1, %2\n\ts_mov_b32 m0, %5\n\ts_nop 0\n\tglobal_load_lds_dword %1, %4\n\ts_mov_b32 m0, %0"
;                      : "=&s"(keep) : "v"(voff), "s"(sb), "s"(l0), "s"(sb2), "s"(l0 + 256u) : "memory");
.LBB0_382:
	s_lshl_b32 s46, s46, 8
	s_ashr_i32 s47, s46, 31
	s_lshl_b32 s48, s20, 8
	s_ashr_i32 s49, s48, 31
	s_lshl_b64 s[50:51], s[46:47], 11
	s_add_u32 s47, s30, s50
	s_addc_u32 s52, s31, s51
	s_lshl_b64 s[50:51], s[48:49], 1
	s_add_u32 s50, s47, s50
	s_addc_u32 s51, s52, s51
	s_add_u32 s52, s50, 0x40000
	s_addc_u32 s53, s51, 0
	s_add_u32 s47, s54, 0x100
	s_addc_u32 s49, s55, 0
	s_add_u32 s54, s44, 0x80
	s_addc_u32 s55, s45, 0
	v_lshl_add_u64 v[130:131], s[54:55], 0, v[180:181]
	v_lshl_add_u64 v[132:133], s[54:55], 0, v[182:183]
	s_mov_b32 s56, 0
	s_mov_b64 s[54:55], 0
	s_waitcnt lgkmcnt(0)
	s_cmp_lg_u32 s69, s56
	s_cbranch_scc1 .Lpeel_body_3
	s_add_i32 s57, s68, 0x100
	s_mov_b32 s73, m0
	s_mov_b32 m0, s68
	s_nop 0
	global_load_lds_dword v210, s[50:51]
	s_mov_b32 m0, s57
	s_nop 0
	global_load_lds_dword v210, s[52:53]
	s_mov_b32 m0, s73
.Lpeel_body_3:
	s_add_i32 s73, s56, 2
	s_add_u32 s57, s44, s54
	s_addc_u32 s74, s45, s55
	s_add_u32 s75, s57, 0x100
	s_addc_u32 s57, s74, 0
	s_add_u32 s74, s47, s54
	s_addc_u32 s76, s49, s55
	s_add_i32 s77, 0, 0x10000
	s_cmp_eq_u32 s15, s56
	s_cselect_b32 s57, s5, s57
	s_cselect_b32 s56, s4, s75
	s_cselect_b32 s75, s43, s76
	s_cselect_b32 s74, s42, s74
	s_add_i32 s76, 0, 0x14000
	v_add_u32_e32 v146, s77, v209
	v_add_u32_e32 v188, s76, v209
	ds_read_b128 v[134:137], v146
	ds_read_b128 v[138:141], v146 offset:1024
	ds_read_b128 v[142:145], v146 offset:2048
	ds_read_b128 v[146:149], v146 offset:3072
	ds_read_b128 v[150:153], v188
	ds_read_b128 v[154:157], v188 offset:1024
	ds_read_b128 v[184:187], v188 offset:2048
	ds_read_b128 v[188:191], v188 offset:3072
	v_lshl_add_u64 v[200:201], v[130:131], 0, s[54:55]
	s_add_i32 m0, s58, 0xc000
	ds_read_b128 v[192:195], v211
	ds_read_b128 v[196:199], v211 offset:1024
	ds_read_b128 v[212:215], v211 offset:2048
	ds_read_b128 v[216:219], v211 offset:3072
	ds_read_b128 v[220:223], v211 offset:4096
	ds_read_b128 v[224:227], v211 offset:5120
	ds_read_b128 v[228:231], v211 offset:6144
	ds_read_b128 v[232:235], v211 offset:7168
	global_load_lds_dwordx4 v[200:201], off
	v_lshl_add_u64 v[200:201], v[132:133], 0, s[54:55]
	s_add_i32 m0, s58, 0xe000
	s_nop 0
	global_load_lds_dwordx4 v[200:201], off
	s_waitcnt vmcnt(8)
	s_waitcnt lgkmcnt(0)
	s_setprio 1
	s_barrier
	v_mfma_f32_16x16x32_bf16 v[126:129], v[134:137], v[192:195], 0
	v_mfma_f32_16x16x32_bf16 v[122:125], v[142:145], v[192:195], 0
	v_mfma_f32_16x16x32_bf16 v[110:113], v[134:137], v[212:215], 0
	v_mfma_f32_16x16x32_bf16 v[106:109], v[142:145], v[212:215], 0
	v_mfma_f32_16x16x32_bf16 v[94:97], v[134:137], v[220:223], 0
	v_mfma_f32_16x16x32_bf16 v[90:93], v[142:145], v[220:223], 0
	v_mfma_f32_16x16x32_bf16 v[76:79], v[134:137], v[228:231], 0
	v_mfma_f32_16x16x32_bf16 v[72:75], v[142:145], v[228:231], 0
	v_mfma_f32_16x16x32_bf16 v[126:129], v[138:141], v[196:199], v[126:129]
	v_mfma_f32_16x16x32_bf16 v[122:125], v[146:149], v[196:199], v[122:125]
	v_mfma_f32_16x16x32_bf16 v[110:113], v[138:141], v[216:219], v[110:113]
	v_mfma_f32_16x16x32_bf16 v[106:109], v[146:149], v[216:219], v[106:109]
	v_mfma_f32_16x16x32_bf16 v[94:97], v[138:141], v[224:227], v[94:97]
	v_mfma_f32_16x16x32_bf16 v[90:93], v[146:149], v[224:227], v[90:93]
	v_mfma_f32_16x16x32_bf16 v[76:79], v[138:141], v[232:235], v[76:79]
	v_mfma_f32_16x16x32_bf16 v[72:75], v[146:149], v[232:235], v[72:75]
	v_mfma_f32_16x16x32_bf16 v[118:121], v[150:153], v[192:195], 0
	v_mfma_f32_16x16x32_bf16 v[114:117], v[184:187], v[192:195], 0
	v_mfma_f32_16x16x32_bf16 v[102:105], v[150:153], v[212:215], 0
	v_mfma_f32_16x16x32_bf16 v[98:101], v[184:187], v[212:215], 0
	v_mfma_f32_16x16x32_bf16 v[86:89], v[150:153], v[220:223], 0
	v_mfma_f32_16x16x32_bf16 v[82:85], v[184:187], v[220:223], 0
	v_mfma_f32_16x16x32_bf16 v[68:71], v[150:153], v[228:231], 0
	v_mfma_f32_16x16x32_bf16 v[64:67], v[184:187], v[228:231], 0
	v_mfma_f32_16x16x32_bf16 v[118:121], v[154:157], v[196:199], v[118:121]
	v_mfma_f32_16x16x32_bf16 v[114:117], v[188:191], v[196:199], v[114:117]
	v_mfma_f32_16x16x32_bf16 v[102:105], v[154:157], v[216:219], v[102:105]
	v_mfma_f32_16x16x32_bf16 v[98:101], v[188:191], v[216:219], v[98:101]
	v_mfma_f32_16x16x32_bf16 v[86:89], v[154:157], v[224:227], v[86:89]
	v_mfma_f32_16x16x32_bf16 v[82:85], v[188:191], v[224:227], v[82:85]
	v_mfma_f32_16x16x32_bf16 v[68:71], v[154:157], v[232:235], v[68:71]
	v_mfma_f32_16x16x32_bf16 v[64:67], v[188:191], v[232:235], v[64:67]
	s_setprio 0
	s_barrier
	s_add_i32 s77, s77, s39
	v_lshl_add_u64 v[200:201], s[74:75], 0, v[176:177]
	s_mov_b32 m0, s77
	ds_read_b128 v[192:195], v211 offset:16384
	ds_read_b128 v[196:199], v211 offset:17408
	ds_read_b128 v[212:215], v211 offset:18432
	ds_read_b128 v[216:219], v211 offset:19456
	ds_read_b128 v[220:223], v211 offset:20480
	ds_read_b128 v[224:227], v211 offset:21504
	ds_read_b128 v[228:231], v211 offset:22528
	ds_read_b128 v[232:235], v211 offset:23552
	global_load_lds_dwordx4 v[200:201], off
	s_add_i32 m0, s77, 0x2000
	v_lshl_add_u64 v[236:237], s[74:75], 0, v[158:159]
	s_add_u32 s74, s74, s14
	s_addc_u32 s75, s75, 0
	s_add_i32 s76, s76, s39
	global_load_lds_dwordx4 v[236:237], off
	v_lshl_add_u64 v[238:239], s[74:75], 0, v[176:177]
	s_mov_b32 m0, s76
	v_lshl_add_u64 v[240:241], s[74:75], 0, v[158:159]
	global_load_lds_dwordx4 v[238:239], off
	s_add_i32 m0, s76, 0x2000
	v_lshl_add_u64 v[242:243], s[56:57], 0, v[178:179]
	global_load_lds_dwordx4 v[240:241], off
	s_mov_b32 m0, s58
	v_lshl_add_u64 v[244:245], s[56:57], 0, v[160:161]
	global_load_lds_dwordx4 v[242:243], off
	s_mov_b32 m0, s59
	s_nop 0
	global_load_lds_dwordx4 v[244:245], off
	s_waitcnt vmcnt(8)
	s_waitcnt lgkmcnt(0)
	s_setprio 1
	s_barrier
; #define PG8_STAGE(bufoff, gbase, voff) do { _Pragma("unroll") for (int _i = 0; _i < 2; ++_i) \
;         __builtin_amdgcn_global_load_lds((const unsigned*)((const char*)(gbase) + (voff)[_i]), (PG8_LAS unsigned*)(lds + (bufoff) + ldsw + _i * 8192), 16, 0, 0); } while (0)
; #define PG8_LDA(dst, b, h) do { _Pragma("unroll") for (int m = 0; m < 4; ++m) _Pragma("unroll") for (int k = 0; k < 2; ++k) dst[m][k] = *(const PG8_LAS bf16x8*)(lds + PG8_SA(b, h) + aoff + m * 2048 + k * 1024); } while (0)
; #define PG8_LDB(dst, b, h) do { _Pragma("unroll") for (int n = 0; n < 2; ++n) _Pragma("unroll") for (int k = 0; k < 2; ++k) dst[n][k] = *(const PG8_LAS bf16x8*)(lds + PG8_SB(b, h) + boff + n * 2048 + k * 1024); } while (0)
; #define PG8_MMA(ai, bj, At, Bt) do { __builtin_amdgcn_s_setprio(1); _Pragma("unroll") for (int m = 0; m < 4; ++m) _Pragma("unroll") for (int n = 0; n < 2; ++n) _Pragma("unroll") for (int k = 0; k < 2; ++k) \
;         acc[ai][bj][m][n] = __builtin_amdgcn_mfma_f32_16x16x32_bf16(Bt[n][k], At[m][k], acc[ai][bj][m][n], 0, 0, 0); __builtin_amdgcn_s_setprio(0); } while (0)
; #define PG8_WAIT_V(n) asm volatile("s_waitcnt vmcnt(" #n ")" ::: "memory")
; #define PG8_WAIT_L(n) asm volatile("s_waitcnt lgkmcnt(" #n ")" ::: "memory")
; #define PG8_BAR __builtin_amdgcn_s_barrier()
; #define PG8_SCHED __builtin_amdgcn_sched_barrier(0)
; template <class Epi, class Sched, bool ALIGN_EPI = false, bool SP2 = false>
; __device__ __forceinline__ void gemm_phase(PG8_LAS unsigned char* lds, const Gemm g, const Sched& S, const Epi& E) {
;     ...
;             PG8_WAIT_V(8); PG8_WAIT_L(0); PG8_BAR; PG8_MMA(1, 0, At, B0); PG8_MMA(1, 1, At, B1); PG8_BAR; PG8_SCHED;
;             PG8_LDB(B0, 1, 0); PG8_LDB(B1, 1, 1); PG8_SCHED; PG8_LDA(At, 1, 0); PG8_STAGE(PG8_SA(0, 1), a2 + hstep, voffA);
;             PG8_WAIT_V(8); PG8_WAIT_L(0); PG8_BAR; PG8_MMA(0, 0, At, B0); PG8_MMA(0, 1, At, B1); PG8_BAR; PG8_SCHED;
	v_mfma_f32_16x16x32_bf16 v[60:63], v[134:137], v[192:195], 0
	v_mfma_f32_16x16x32_bf16 v[56:59], v[142:145], v[192:195], 0
	v_mfma_f32_16x16x32_bf16 v[44:47], v[134:137], v[212:215], 0
	v_mfma_f32_16x16x32_bf16 v[40:43], v[142:145], v[212:215], 0
	v_mfma_f32_16x16x32_bf16 v[28:31], v[134:137], v[220:223], 0
	v_mfma_f32_16x16x32_bf16 v[24:27], v[142:145], v[220:223], 0
	v_mfma_f32_16x16x32_bf16 v[12:15], v[134:137], v[228:231], 0
	v_mfma_f32_16x16x32_bf16 v[8:11], v[142:145], v[228:231], 0
	v_mfma_f32_16x16x32_bf16 v[60:63], v[138:141], v[196:199], v[60:63]
	v_mfma_f32_16x16x32_bf16 v[56:59], v[146:149], v[196:199], v[56:59]
	v_mfma_f32_16x16x32_bf16 v[44:47], v[138:141], v[216:219], v[44:47]
	v_mfma_f32_16x16x32_bf16 v[40:43], v[146:149], v[216:219], v[40:43]
	v_mfma_f32_16x16x32_bf16 v[28:31], v[138:141], v[224:227], v[28:31]
	v_mfma_f32_16x16x32_bf16 v[24:27], v[146:149], v[224:227], v[24:27]
	v_mfma_f32_16x16x32_bf16 v[12:15], v[138:141], v[232:235], v[12:15]
	v_mfma_f32_16x16x32_bf16 v[8:11], v[146:149], v[232:235], v[8:11]
	v_mfma_f32_16x16x32_bf16 v[52:55], v[150:153], v[192:195], 0
	v_mfma_f32_16x16x32_bf16 v[48:51], v[184:187], v[192:195], 0
	v_mfma_f32_16x16x32_bf16 v[36:39], v[150:153], v[212:215], 0
	v_mfma_f32_16x16x32_bf16 v[32:35], v[184:187], v[212:215], 0
	v_mfma_f32_16x16x32_bf16 v[20:23], v[150:153], v[220:223], 0
	v_mfma_f32_16x16x32_bf16 v[16:19], v[184:187], v[220:223], 0
	v_mfma_f32_16x16x32_bf16 v[4:7], v[150:153], v[228:231], 0
	v_mfma_f32_16x16x32_bf16 v[0:3], v[184:187], v[228:231], 0
	v_mfma_f32_16x16x32_bf16 v[52:55], v[154:157], v[196:199], v[52:55]
	v_mfma_f32_16x16x32_bf16 v[48:51], v[188:191], v[196:199], v[48:51]
	v_mfma_f32_16x16x32_bf16 v[36:39], v[154:157], v[216:219], v[36:39]
	v_mfma_f32_16x16x32_bf16 v[32:35], v[188:191], v[216:219], v[32:35]
	v_mfma_f32_16x16x32_bf16 v[20:23], v[154:157], v[224:227], v[20:23]
	v_mfma_f32_16x16x32_bf16 v[16:19], v[188:191], v[224:227], v[16:19]
	v_mfma_f32_16x16x32_bf16 v[4:7], v[154:157], v[232:235], v[4:7]
	v_mfma_f32_16x16x32_bf16 v[0:3], v[188:191], v[232:235], v[0:3]
	s_setprio 0
	s_barrier
	s_add_i32 s74, 0, 0x18000
	s_add_i32 s75, 0, 0x1c000
	v_add_u32_e32 v146, s74, v209
	v_add_u32_e32 v188, s75, v209
	ds_read_b128 v[134:137], v146
	ds_read_b128 v[138:141], v146 offset:1024
	ds_read_b128 v[142:145], v146 offset:2048
	ds_read_b128 v[146:149], v146 offset:3072
	ds_read_b128 v[150:153], v188
	ds_read_b128 v[154:157], v188 offset:1024
	ds_read_b128 v[184:187], v188 offset:2048
	ds_read_b128 v[188:191], v188 offset:3072
	s_add_u32 s56, s56, s14
	s_addc_u32 s57, s57, 0
	s_mov_b32 m0, s60
	v_lshl_add_u64 v[246:247], s[56:57], 0, v[178:179]
	ds_read_b128 v[192:195], v211 offset:32768
	ds_read_b128 v[196:199], v211 offset:33792
	ds_read_b128 v[212:215], v211 offset:34816
	ds_read_b128 v[216:219], v211 offset:35840
	ds_read_b128 v[220:223], v211 offset:36864
	ds_read_b128 v[224:227], v211 offset:37888
	ds_read_b128 v[228:231], v211 offset:38912
	ds_read_b128 v[232:235], v211 offset:39936
	global_load_lds_dwordx4 v[246:247], off
	v_lshl_add_u64 v[246:247], s[56:57], 0, v[160:161]
	s_mov_b32 m0, s61
	s_nop 0
	global_load_lds_dwordx4 v[246:247], off
	s_waitcnt vmcnt(8)
	s_waitcnt lgkmcnt(0)
	s_setprio 1
	s_barrier
	v_mfma_f32_16x16x32_bf16 v[126:129], v[134:137], v[192:195], v[126:129]
	v_mfma_f32_16x16x32_bf16 v[122:125], v[142:145], v[192:195], v[122:125]
	v_mfma_f32_16x16x32_bf16 v[110:113], v[134:137], v[212:215], v[110:113]
	v_mfma_f32_16x16x32_bf16 v[106:109], v[142:145], v[212:215], v[106:109]
	v_mfma_f32_16x16x32_bf16 v[94:97], v[134:137], v[220:223], v[94:97]
	v_mfma_f32_16x16x32_bf16 v[90:93], v[142:145], v[220:223], v[90:93]
	v_mfma_f32_16x16x32_bf16 v[76:79], v[134:137], v[228:231], v[76:79]
	v_mfma_f32_16x16x32_bf16 v[72:75], v[142:145], v[228:231], v[72:75]
	v_mfma_f32_16x16x32_bf16 v[126:129], v[138:141], v[196:199], v[126:129]
	v_mfma_f32_16x16x32_bf16 v[122:125], v[146:149], v[196:199], v[122:125]
	v_mfma_f32_16x16x32_bf16 v[110:113], v[138:141], v[216:219], v[110:113]
	v_mfma_f32_16x16x32_bf16 v[106:109], v[146:149], v[216:219], v[106:109]
	v_mfma_f32_16x16x32_bf16 v[94:97], v[138:141], v[224:227], v[94:97]
	v_mfma_f32_16x16x32_bf16 v[90:93], v[146:149], v[224:227], v[90:93]
	v_mfma_f32_16x16x32_bf16 v[76:79], v[138:141], v[232:235], v[76:79]
	v_mfma_f32_16x16x32_bf16 v[72:75], v[146:149], v[232:235], v[72:75]
	v_mfma_f32_16x16x32_bf16 v[118:121], v[150:153], v[192:195], v[118:121]
	v_mfma_f32_16x16x32_bf16 v[114:117], v[184:187], v[192:195], v[114:117]
	v_mfma_f32_16x16x32_bf16 v[102:105], v[150:153], v[212:215], v[102:105]
	v_mfma_f32_16x16x32_bf16 v[98:101], v[184:187], v[212:215], v[98:101]
	v_mfma_f32_16x16x32_bf16 v[86:89], v[150:153], v[220:223], v[86:89]
	v_mfma_f32_16x16x32_bf16 v[82:85], v[184:187], v[220:223], v[82:85]
	v_mfma_f32_16x16x32_bf16 v[68:71], v[150:153], v[228:231], v[68:71]
	v_mfma_f32_16x16x32_bf16 v[64:67], v[184:187], v[228:231], v[64:67]
	v_mfma_f32_16x16x32_bf16 v[118:121], v[154:157], v[196:199], v[118:121]
	v_mfma_f32_16x16x32_bf16 v[114:117], v[188:191], v[196:199], v[114:117]
	v_mfma_f32_16x16x32_bf16 v[102:105], v[154:157], v[216:219], v[102:105]
	v_mfma_f32_16x16x32_bf16 v[98:101], v[188:191], v[216:219], v[98:101]
	v_mfma_f32_16x16x32_bf16 v[86:89], v[154:157], v[224:227], v[86:89]
	v_mfma_f32_16x16x32_bf16 v[82:85], v[188:191], v[224:227], v[82:85]
	v_mfma_f32_16x16x32_bf16 v[68:71], v[154:157], v[232:235], v[68:71]
	v_mfma_f32_16x16x32_bf16 v[64:67], v[188:191], v[232:235], v[64:67]
	s_setprio 0
	s_barrier
; #define PG8_STAGE(bufoff, gbase, voff) do { _Pragma("unroll") for (int _i = 0; _i < 2; ++_i) \
;         __builtin_amdgcn_global_load_lds((const unsigned*)((const char*)(gbase) + (voff)[_i]), (PG8_LAS unsigned*)(lds + (bufoff) + ldsw + _i * 8192), 16, 0, 0); } while (0)
; #define PG8_LDA(dst, b, h) do { _Pragma("unroll") for (int m = 0; m < 4; ++m) _Pragma("unroll") for (int k = 0; k < 2; ++k) dst[m][k] = *(const PG8_LAS bf16x8*)(lds + PG8_SA(b, h) + aoff + m * 2048 + k * 1024); } while (0)
; #define PG8_MMA(ai, bj, At, Bt) do { __builtin_amdgcn_s_setprio(1); _Pragma("unroll") for (int m = 0; m < 4; ++m) _Pragma("unroll") for (int n = 0; n < 2; ++n) _Pragma("unroll") for (int k = 0; k < 2; ++k) \
;         acc[ai][bj][m][n] = __builtin_amdgcn_mfma_f32_16x16x32_bf16(Bt[n][k], At[m][k], acc[ai][bj][m][n], 0, 0, 0); __builtin_amdgcn_s_setprio(0); } while (0)
; #define PG8_WAIT_V(n) asm volatile("s_waitcnt vmcnt(" #n ")" ::: "memory")
; #define PG8_WAIT_L(n) asm volatile("s_waitcnt lgkmcnt(" #n ")" ::: "memory")
; #define PG8_BAR __builtin_amdgcn_s_barrier()
; #define PG8_SCHED __builtin_amdgcn_sched_barrier(0)
; template <class Epi, class Sched, bool ALIGN_EPI = false, bool SP2 = false>
; __device__ __forceinline__ void gemm_phase(PG8_LAS unsigned char* lds, const Gemm g, const Sched& S, const Epi& E) {
;     ...
;             PG8_LDA(At, 1, 1); PG8_STAGE(PG8_SB(1, 0), b3, voffB); PG8_STAGE(PG8_SB(1, 1), b3 + hstep, voffB); PG8_STAGE(PG8_SA(1, 0), a3, voffA);
;             PG8_WAIT_V(8); PG8_WAIT_L(0); PG8_BAR; PG8_MMA(1, 0, At, B0); PG8_MMA(1, 1, At, B1); PG8_BAR; PG8_SCHED;
	s_add_i32 s56, s74, s39
	v_lshl_add_u64 v[200:201], v[200:201], 0, s[40:41]
	s_mov_b32 m0, s56
	ds_read_b128 v[192:195], v211 offset:49152
	ds_read_b128 v[196:199], v211 offset:50176
	ds_read_b128 v[212:215], v211 offset:51200
	ds_read_b128 v[216:219], v211 offset:52224
	ds_read_b128 v[220:223], v211 offset:53248
	ds_read_b128 v[224:227], v211 offset:54272
	ds_read_b128 v[228:231], v211 offset:55296
	ds_read_b128 v[232:235], v211 offset:56320
	global_load_lds_dwordx4 v[200:201], off
	v_lshl_add_u64 v[200:201], v[236:237], 0, s[40:41]
	s_add_i32 m0, s56, 0x2000
	s_add_i32 s56, s75, s39
	global_load_lds_dwordx4 v[200:201], off
	v_lshl_add_u64 v[200:201], v[238:239], 0, s[40:41]
	s_mov_b32 m0, s56
	s_nop 0
	global_load_lds_dwordx4 v[200:201], off
	v_lshl_add_u64 v[200:201], v[240:241], 0, s[40:41]
	s_add_i32 m0, s56, 0x2000
	s_nop 0
	global_load_lds_dwordx4 v[200:201], off
	v_lshl_add_u64 v[200:201], v[242:243], 0, s[40:41]
	s_mov_b32 m0, s66
	s_nop 0
	global_load_lds_dwordx4 v[200:201], off
	v_lshl_add_u64 v[200:201], v[244:245], 0, s[40:41]
	s_mov_b32 m0, s67
	s_nop 0
	global_load_lds_dwordx4 v[200:201], off
	s_waitcnt vmcnt(8)
	s_waitcnt lgkmcnt(0)
	s_setprio 1
	s_barrier
	v_mfma_f32_16x16x32_bf16 v[60:63], v[134:137], v[192:195], v[60:63]
	v_mfma_f32_16x16x32_bf16 v[56:59], v[142:145], v[192:195], v[56:59]
	v_mfma_f32_16x16x32_bf16 v[44:47], v[134:137], v[212:215], v[44:47]
	v_mfma_f32_16x16x32_bf16 v[40:43], v[142:145], v[212:215], v[40:43]
	v_mfma_f32_16x16x32_bf16 v[28:31], v[134:137], v[220:223], v[28:31]
	v_mfma_f32_16x16x32_bf16 v[24:27], v[142:145], v[220:223], v[24:27]
	v_mfma_f32_16x16x32_bf16 v[12:15], v[134:137], v[228:231], v[12:15]
	v_mfma_f32_16x16x32_bf16 v[8:11], v[142:145], v[228:231], v[8:11]
	v_mfma_f32_16x16x32_bf16 v[60:63], v[138:141], v[196:199], v[60:63]
	v_mfma_f32_16x16x32_bf16 v[56:59], v[146:149], v[196:199], v[56:59]
	v_mfma_f32_16x16x32_bf16 v[44:47], v[138:141], v[216:219], v[44:47]
	v_mfma_f32_16x16x32_bf16 v[40:43], v[146:149], v[216:219], v[40:43]
	v_mfma_f32_16x16x32_bf16 v[28:31], v[138:141], v[224:227], v[28:31]
	v_mfma_f32_16x16x32_bf16 v[24:27], v[146:149], v[224:227], v[24:27]
	v_mfma_f32_16x16x32_bf16 v[12:15], v[138:141], v[232:235], v[12:15]
	v_mfma_f32_16x16x32_bf16 v[8:11], v[146:149], v[232:235], v[8:11]
	v_mfma_f32_16x16x32_bf16 v[52:55], v[150:153], v[192:195], v[52:55]
	v_mfma_f32_16x16x32_bf16 v[48:51], v[184:187], v[192:195], v[48:51]
	v_mfma_f32_16x16x32_bf16 v[36:39], v[150:153], v[212:215], v[36:39]
	v_mfma_f32_16x16x32_bf16 v[32:35], v[184:187], v[212:215], v[32:35]
	v_mfma_f32_16x16x32_bf16 v[20:23], v[150:153], v[220:223], v[20:23]
	v_mfma_f32_16x16x32_bf16 v[16:19], v[184:187], v[220:223], v[16:19]
	v_mfma_f32_16x16x32_bf16 v[4:7], v[150:153], v[228:231], v[4:7]
	v_mfma_f32_16x16x32_bf16 v[0:3], v[184:187], v[228:231], v[0:3]
	v_mfma_f32_16x16x32_bf16 v[52:55], v[154:157], v[196:199], v[52:55]
	v_mfma_f32_16x16x32_bf16 v[48:51], v[188:191], v[196:199], v[48:51]
	v_mfma_f32_16x16x32_bf16 v[36:39], v[154:157], v[216:219], v[36:39]
	v_mfma_f32_16x16x32_bf16 v[32:35], v[188:191], v[216:219], v[32:35]
	v_mfma_f32_16x16x32_bf16 v[20:23], v[154:157], v[224:227], v[20:23]
	v_mfma_f32_16x16x32_bf16 v[16:19], v[188:191], v[224:227], v[16:19]
	v_mfma_f32_16x16x32_bf16 v[4:7], v[154:157], v[232:235], v[4:7]
	v_mfma_f32_16x16x32_bf16 v[0:3], v[188:191], v[232:235], v[0:3]
	s_setprio 0
	s_barrier
	s_add_u32 s54, s54, 0x100
	s_addc_u32 s55, s55, 0
	s_cmp_ge_u32 s73, s63
	s_mov_b32 s56, s73
	s_cbranch_scc1 .LBB0_386
	s_branch .LBB0_384
